# main loops: dropped the no-op s_setprio 0/1 pair inside each MMA segment and the redundant lgkmcnt(0) wait before its first MFMA
# baseline (speedup 1.0000x reference)
.LBB0_198:
	ds_read_b128 v[18:21], v176
	ds_read_b128 v[22:25], v176 offset:1024
	ds_read_b128 v[34:37], v176 offset:2048
	ds_read_b128 v[38:41], v176 offset:3072
	ds_read_b128 v[164:167], v177
	ds_read_b128 v[168:171], v177 offset:1024
	ds_read_b128 v[180:183], v177 offset:2048
	ds_read_b128 v[184:187], v177 offset:3072
	s_add_u32 s8, s0, 0xfffc0080
	s_addc_u32 s9, s1, -1
	s_cmp_eq_u32 s96, 12
	s_cselect_b32 s11, s7, s9
	s_cselect_b32 s10, s40, s8
	s_cselect_b32 s9, s41, s93
	s_cselect_b32 s8, s65, s67
	v_lshl_add_u64 v[172:173], s[0:1], 0, v[156:157]
	s_add_i32 m0, s21, 0xc000
	ds_read_b128 v[188:191], v178
	ds_read_b128 v[192:195], v178 offset:1024
	ds_read_b128 v[196:199], v178 offset:2048
	ds_read_b128 v[200:203], v178 offset:3072
	ds_read_b128 v[204:207], v178 offset:4096
	ds_read_b128 v[208:211], v178 offset:5120
	ds_read_b128 v[212:215], v178 offset:6144
	ds_read_b128 v[220:223], v178 offset:7168
	global_load_lds_dwordx4 v[172:173], off
	v_lshl_add_u64 v[172:173], s[0:1], 0, v[158:159]
	s_add_i32 m0, s21, 0xe000
	s_nop 0
	global_load_lds_dwordx4 v[172:173], off
	s_waitcnt vmcnt(8)
	s_waitcnt lgkmcnt(0)
	s_barrier
	s_setprio 1
	v_mfma_f32_16x16x32_bf16 v[142:145], v[18:21], v[188:191], v[142:145]
	v_mfma_f32_16x16x32_bf16 v[138:141], v[34:37], v[188:191], v[138:141]
	v_mfma_f32_16x16x32_bf16 v[126:129], v[18:21], v[196:199], v[126:129]
	v_mfma_f32_16x16x32_bf16 v[122:125], v[34:37], v[196:199], v[122:125]
	v_mfma_f32_16x16x32_bf16 v[110:113], v[18:21], v[204:207], v[110:113]
	v_mfma_f32_16x16x32_bf16 v[106:109], v[34:37], v[204:207], v[106:109]
	v_mfma_f32_16x16x32_bf16 v[94:97], v[18:21], v[212:215], v[94:97]
	v_mfma_f32_16x16x32_bf16 v[90:93], v[34:37], v[212:215], v[90:93]
	v_mfma_f32_16x16x32_bf16 v[142:145], v[22:25], v[192:195], v[142:145]
	v_mfma_f32_16x16x32_bf16 v[138:141], v[38:41], v[192:195], v[138:141]
	v_mfma_f32_16x16x32_bf16 v[126:129], v[22:25], v[200:203], v[126:129]
	v_mfma_f32_16x16x32_bf16 v[122:125], v[38:41], v[200:203], v[122:125]
	v_mfma_f32_16x16x32_bf16 v[110:113], v[22:25], v[208:211], v[110:113]
	v_mfma_f32_16x16x32_bf16 v[106:109], v[38:41], v[208:211], v[106:109]
	v_mfma_f32_16x16x32_bf16 v[94:97], v[22:25], v[220:223], v[94:97]
	v_mfma_f32_16x16x32_bf16 v[90:93], v[38:41], v[220:223], v[90:93]
	v_mfma_f32_16x16x32_bf16 v[134:137], v[164:167], v[188:191], v[134:137]
	v_mfma_f32_16x16x32_bf16 v[130:133], v[180:183], v[188:191], v[130:133]
	v_mfma_f32_16x16x32_bf16 v[118:121], v[164:167], v[196:199], v[118:121]
	v_mfma_f32_16x16x32_bf16 v[114:117], v[180:183], v[196:199], v[114:117]
	v_mfma_f32_16x16x32_bf16 v[102:105], v[164:167], v[204:207], v[102:105]
	v_mfma_f32_16x16x32_bf16 v[98:101], v[180:183], v[204:207], v[98:101]
	v_mfma_f32_16x16x32_bf16 v[86:89], v[164:167], v[212:215], v[86:89]
	v_mfma_f32_16x16x32_bf16 v[82:85], v[180:183], v[212:215], v[82:85]
	v_mfma_f32_16x16x32_bf16 v[134:137], v[168:171], v[192:195], v[134:137]
	v_mfma_f32_16x16x32_bf16 v[130:133], v[184:187], v[192:195], v[130:133]
	v_mfma_f32_16x16x32_bf16 v[118:121], v[168:171], v[200:203], v[118:121]
	v_mfma_f32_16x16x32_bf16 v[114:117], v[184:187], v[200:203], v[114:117]
	v_mfma_f32_16x16x32_bf16 v[102:105], v[168:171], v[208:211], v[102:105]
	v_mfma_f32_16x16x32_bf16 v[98:101], v[184:187], v[208:211], v[98:101]
	v_mfma_f32_16x16x32_bf16 v[86:89], v[168:171], v[220:223], v[86:89]
	v_mfma_f32_16x16x32_bf16 v[82:85], v[184:187], v[220:223], v[82:85]
	s_setprio 0
	s_barrier
	s_add_i32 s97, s45, s35
	v_lshl_add_u64 v[172:173], s[8:9], 0, v[148:149]
	s_mov_b32 m0, s97
	ds_read_b128 v[188:191], v178 offset:16384
	ds_read_b128 v[192:195], v178 offset:17408
	ds_read_b128 v[196:199], v178 offset:18432
	ds_read_b128 v[200:203], v178 offset:19456
	ds_read_b128 v[204:207], v178 offset:20480
	ds_read_b128 v[208:211], v178 offset:21504
	ds_read_b128 v[212:215], v178 offset:22528
	ds_read_b128 v[220:223], v178 offset:23552
	global_load_lds_dwordx4 v[172:173], off
	s_add_i32 m0, s97, 0x2000
	s_add_u32 vcc_lo, s8, 0x40000
	v_lshl_add_u64 v[216:217], s[8:9], 0, v[152:153]
	s_addc_u32 vcc_hi, s9, 0
	s_add_i32 s97, s92, s35
	global_load_lds_dwordx4 v[216:217], off
	v_lshl_add_u64 v[224:225], vcc, 0, v[148:149]
	s_mov_b32 m0, s97
	v_lshl_add_u64 v[226:227], s[10:11], 0, v[150:151]
	global_load_lds_dwordx4 v[224:225], off
	v_lshl_add_u64 v[224:225], vcc, 0, v[152:153]
	s_add_i32 m0, s97, 0x2000
	s_nop 0
	global_load_lds_dwordx4 v[224:225], off
	v_lshl_add_u64 v[224:225], s[10:11], 0, v[146:147]
	s_mov_b32 m0, s21
	s_nop 0
	global_load_lds_dwordx4 v[224:225], off
	s_mov_b32 m0, s37
	s_nop 0
	global_load_lds_dwordx4 v[226:227], off
	s_waitcnt vmcnt(8)
	s_waitcnt lgkmcnt(0)
	s_barrier
	s_setprio 1
	v_mfma_f32_16x16x32_bf16 v[78:81], v[18:21], v[188:191], v[78:81]
	v_mfma_f32_16x16x32_bf16 v[74:77], v[34:37], v[188:191], v[74:77]
	v_mfma_f32_16x16x32_bf16 v[62:65], v[18:21], v[196:199], v[62:65]
	v_mfma_f32_16x16x32_bf16 v[58:61], v[34:37], v[196:199], v[58:61]
	v_mfma_f32_16x16x32_bf16 v[46:49], v[18:21], v[204:207], v[46:49]
	v_mfma_f32_16x16x32_bf16 v[42:45], v[34:37], v[204:207], v[42:45]
	v_mfma_f32_16x16x32_bf16 v[14:17], v[18:21], v[212:215], v[14:17]
	v_mfma_f32_16x16x32_bf16 v[10:13], v[34:37], v[212:215], v[10:13]
	v_mfma_f32_16x16x32_bf16 v[78:81], v[22:25], v[192:195], v[78:81]
	v_mfma_f32_16x16x32_bf16 v[74:77], v[38:41], v[192:195], v[74:77]
	v_mfma_f32_16x16x32_bf16 v[62:65], v[22:25], v[200:203], v[62:65]
	v_mfma_f32_16x16x32_bf16 v[58:61], v[38:41], v[200:203], v[58:61]
	v_mfma_f32_16x16x32_bf16 v[46:49], v[22:25], v[208:211], v[46:49]
	v_mfma_f32_16x16x32_bf16 v[42:45], v[38:41], v[208:211], v[42:45]
	v_mfma_f32_16x16x32_bf16 v[14:17], v[22:25], v[220:223], v[14:17]
	v_mfma_f32_16x16x32_bf16 v[10:13], v[38:41], v[220:223], v[10:13]
	v_mfma_f32_16x16x32_bf16 v[30:33], v[164:167], v[204:207], v[30:33]
	v_mfma_f32_16x16x32_bf16 v[26:29], v[180:183], v[204:207], v[26:29]
	v_mfma_f32_16x16x32_bf16 v[6:9], v[164:167], v[212:215], v[6:9]
	v_mfma_f32_16x16x32_bf16 v[2:5], v[180:183], v[212:215], v[2:5]
	v_mfma_f32_16x16x32_bf16 v[18:21], v[164:167], v[188:191], v[70:73]
	v_mfma_f32_16x16x32_bf16 v[22:25], v[180:183], v[188:191], v[66:69]
	v_mfma_f32_16x16x32_bf16 v[34:37], v[164:167], v[196:199], v[54:57]
	v_mfma_f32_16x16x32_bf16 v[38:41], v[180:183], v[196:199], v[50:53]
	v_mfma_f32_16x16x32_bf16 v[30:33], v[168:171], v[208:211], v[30:33]
	v_mfma_f32_16x16x32_bf16 v[26:29], v[184:187], v[208:211], v[26:29]
	v_mfma_f32_16x16x32_bf16 v[6:9], v[168:171], v[220:223], v[6:9]
	v_mfma_f32_16x16x32_bf16 v[2:5], v[184:187], v[220:223], v[2:5]
	v_mfma_f32_16x16x32_bf16 v[18:21], v[168:171], v[192:195], v[18:21]
	v_mfma_f32_16x16x32_bf16 v[22:25], v[184:187], v[192:195], v[22:25]
	v_mfma_f32_16x16x32_bf16 v[34:37], v[168:171], v[200:203], v[34:37]
	v_mfma_f32_16x16x32_bf16 v[38:41], v[184:187], v[200:203], v[38:41]
	s_setprio 0
	s_barrier
	s_add_i32 s97, 0, 0x18000
	s_add_i32 vcc_lo, 0, 0x1c000
	v_add_u32_e32 v70, s97, v174
	v_add_u32_e32 v155, vcc_lo, v174
	ds_read_b128 v[50:53], v70
	ds_read_b128 v[54:57], v70 offset:1024
	ds_read_b128 v[66:69], v70 offset:2048
	ds_read_b128 v[70:73], v70 offset:3072
	ds_read_b128 v[164:167], v155
	ds_read_b128 v[168:171], v155 offset:1024
	ds_read_b128 v[180:183], v155 offset:2048
	ds_read_b128 v[184:187], v155 offset:3072
	s_add_u32 s10, s10, 0x40000
	s_addc_u32 s11, s11, 0
	s_mov_b32 m0, s39
	v_lshl_add_u64 v[228:229], s[10:11], 0, v[146:147]
	ds_read_b128 v[188:191], v178 offset:32768
	ds_read_b128 v[192:195], v178 offset:33792
	ds_read_b128 v[196:199], v178 offset:34816
	ds_read_b128 v[200:203], v178 offset:35840
	ds_read_b128 v[204:207], v178 offset:36864
	ds_read_b128 v[208:211], v178 offset:37888
	ds_read_b128 v[212:215], v178 offset:38912
	ds_read_b128 v[220:223], v178 offset:39936
	global_load_lds_dwordx4 v[228:229], off
	v_lshl_add_u64 v[228:229], s[10:11], 0, v[150:151]
	s_mov_b32 m0, s51
	s_nop 0
	global_load_lds_dwordx4 v[228:229], off
	s_waitcnt vmcnt(8)
	s_waitcnt lgkmcnt(0)
	s_barrier
	s_setprio 1
	v_mfma_f32_16x16x32_bf16 v[142:145], v[50:53], v[188:191], v[142:145]
	v_mfma_f32_16x16x32_bf16 v[138:141], v[66:69], v[188:191], v[138:141]
	v_mfma_f32_16x16x32_bf16 v[126:129], v[50:53], v[196:199], v[126:129]
	v_mfma_f32_16x16x32_bf16 v[122:125], v[66:69], v[196:199], v[122:125]
	v_mfma_f32_16x16x32_bf16 v[110:113], v[50:53], v[204:207], v[110:113]
	v_mfma_f32_16x16x32_bf16 v[106:109], v[66:69], v[204:207], v[106:109]
	v_mfma_f32_16x16x32_bf16 v[94:97], v[50:53], v[212:215], v[94:97]
	v_mfma_f32_16x16x32_bf16 v[90:93], v[66:69], v[212:215], v[90:93]
	v_mfma_f32_16x16x32_bf16 v[142:145], v[54:57], v[192:195], v[142:145]
	v_mfma_f32_16x16x32_bf16 v[138:141], v[70:73], v[192:195], v[138:141]
	v_mfma_f32_16x16x32_bf16 v[126:129], v[54:57], v[200:203], v[126:129]
	v_mfma_f32_16x16x32_bf16 v[122:125], v[70:73], v[200:203], v[122:125]
	v_mfma_f32_16x16x32_bf16 v[110:113], v[54:57], v[208:211], v[110:113]
	v_mfma_f32_16x16x32_bf16 v[106:109], v[70:73], v[208:211], v[106:109]
	v_mfma_f32_16x16x32_bf16 v[94:97], v[54:57], v[220:223], v[94:97]
	v_mfma_f32_16x16x32_bf16 v[90:93], v[70:73], v[220:223], v[90:93]
	v_mfma_f32_16x16x32_bf16 v[134:137], v[164:167], v[188:191], v[134:137]
	v_mfma_f32_16x16x32_bf16 v[130:133], v[180:183], v[188:191], v[130:133]
	v_mfma_f32_16x16x32_bf16 v[118:121], v[164:167], v[196:199], v[118:121]
	v_mfma_f32_16x16x32_bf16 v[114:117], v[180:183], v[196:199], v[114:117]
	v_mfma_f32_16x16x32_bf16 v[102:105], v[164:167], v[204:207], v[102:105]
	v_mfma_f32_16x16x32_bf16 v[98:101], v[180:183], v[204:207], v[98:101]
	v_mfma_f32_16x16x32_bf16 v[86:89], v[164:167], v[212:215], v[86:89]
	v_mfma_f32_16x16x32_bf16 v[82:85], v[180:183], v[212:215], v[82:85]
	v_mfma_f32_16x16x32_bf16 v[134:137], v[168:171], v[192:195], v[134:137]
	v_mfma_f32_16x16x32_bf16 v[130:133], v[184:187], v[192:195], v[130:133]
	v_mfma_f32_16x16x32_bf16 v[118:121], v[168:171], v[200:203], v[118:121]
	v_mfma_f32_16x16x32_bf16 v[114:117], v[184:187], v[200:203], v[114:117]
	v_mfma_f32_16x16x32_bf16 v[102:105], v[168:171], v[208:211], v[102:105]
	v_mfma_f32_16x16x32_bf16 v[98:101], v[184:187], v[208:211], v[98:101]
	v_mfma_f32_16x16x32_bf16 v[86:89], v[168:171], v[220:223], v[86:89]
	v_mfma_f32_16x16x32_bf16 v[82:85], v[184:187], v[220:223], v[82:85]
	s_setprio 0
	s_barrier
	s_add_i32 s10, s97, s35
	v_lshl_add_u64 v[172:173], v[172:173], 0, s[28:29]
	s_mov_b32 m0, s10
	ds_read_b128 v[188:191], v178 offset:49152
	ds_read_b128 v[192:195], v178 offset:50176
	ds_read_b128 v[196:199], v178 offset:51200
	ds_read_b128 v[200:203], v178 offset:52224
	ds_read_b128 v[204:207], v178 offset:53248
	ds_read_b128 v[208:211], v178 offset:54272
	ds_read_b128 v[212:215], v178 offset:55296
	ds_read_b128 v[220:223], v178 offset:56320
	global_load_lds_dwordx4 v[172:173], off
	s_add_i32 m0, s10, 0x2000
	s_add_u32 s8, s8, 0x40080
	v_lshl_add_u64 v[172:173], v[216:217], 0, s[28:29]
	s_addc_u32 s9, s9, 0
	s_add_i32 s10, vcc_lo, s35
	global_load_lds_dwordx4 v[172:173], off
	v_lshl_add_u64 v[172:173], s[8:9], 0, v[148:149]
	s_mov_b32 m0, s10
	s_nop 0
	global_load_lds_dwordx4 v[172:173], off
	v_lshl_add_u64 v[172:173], s[8:9], 0, v[152:153]
	s_add_i32 m0, s10, 0x2000
	s_nop 0
	global_load_lds_dwordx4 v[172:173], off
	v_lshl_add_u64 v[172:173], v[224:225], 0, s[28:29]
	s_mov_b32 m0, s57
	s_nop 0
	global_load_lds_dwordx4 v[172:173], off
	v_lshl_add_u64 v[172:173], v[226:227], 0, s[28:29]
	s_mov_b32 m0, s59
	s_nop 0
	global_load_lds_dwordx4 v[172:173], off
	s_waitcnt vmcnt(8)
	s_waitcnt lgkmcnt(0)
	s_barrier
	s_setprio 1
	v_mfma_f32_16x16x32_bf16 v[78:81], v[50:53], v[188:191], v[78:81]
	v_mfma_f32_16x16x32_bf16 v[74:77], v[66:69], v[188:191], v[74:77]
	v_mfma_f32_16x16x32_bf16 v[62:65], v[50:53], v[196:199], v[62:65]
	v_mfma_f32_16x16x32_bf16 v[58:61], v[66:69], v[196:199], v[58:61]
	v_mfma_f32_16x16x32_bf16 v[46:49], v[50:53], v[204:207], v[46:49]
	v_mfma_f32_16x16x32_bf16 v[42:45], v[66:69], v[204:207], v[42:45]
	v_mfma_f32_16x16x32_bf16 v[14:17], v[50:53], v[212:215], v[14:17]
	v_mfma_f32_16x16x32_bf16 v[10:13], v[66:69], v[212:215], v[10:13]
	v_mfma_f32_16x16x32_bf16 v[78:81], v[54:57], v[192:195], v[78:81]
	v_mfma_f32_16x16x32_bf16 v[74:77], v[70:73], v[192:195], v[74:77]
	v_mfma_f32_16x16x32_bf16 v[62:65], v[54:57], v[200:203], v[62:65]
	v_mfma_f32_16x16x32_bf16 v[58:61], v[70:73], v[200:203], v[58:61]
	v_mfma_f32_16x16x32_bf16 v[46:49], v[54:57], v[208:211], v[46:49]
	v_mfma_f32_16x16x32_bf16 v[42:45], v[70:73], v[208:211], v[42:45]
	v_mfma_f32_16x16x32_bf16 v[14:17], v[54:57], v[220:223], v[14:17]
	v_mfma_f32_16x16x32_bf16 v[10:13], v[70:73], v[220:223], v[10:13]
	v_mfma_f32_16x16x32_bf16 v[18:21], v[164:167], v[188:191], v[18:21]
	v_mfma_f32_16x16x32_bf16 v[70:73], v[168:171], v[192:195], v[18:21]
	v_mfma_f32_16x16x32_bf16 v[18:21], v[180:183], v[188:191], v[22:25]
	v_mfma_f32_16x16x32_bf16 v[66:69], v[184:187], v[192:195], v[18:21]
	v_mfma_f32_16x16x32_bf16 v[18:21], v[164:167], v[196:199], v[34:37]
	v_mfma_f32_16x16x32_bf16 v[54:57], v[168:171], v[200:203], v[18:21]
	v_mfma_f32_16x16x32_bf16 v[18:21], v[180:183], v[196:199], v[38:41]
	v_mfma_f32_16x16x32_bf16 v[50:53], v[184:187], v[200:203], v[18:21]
	v_mfma_f32_16x16x32_bf16 v[18:21], v[164:167], v[204:207], v[30:33]
	v_mfma_f32_16x16x32_bf16 v[30:33], v[168:171], v[208:211], v[18:21]
	v_mfma_f32_16x16x32_bf16 v[18:21], v[180:183], v[204:207], v[26:29]
	v_mfma_f32_16x16x32_bf16 v[6:9], v[164:167], v[212:215], v[6:9]
	v_mfma_f32_16x16x32_bf16 v[2:5], v[180:183], v[212:215], v[2:5]
	v_mfma_f32_16x16x32_bf16 v[26:29], v[184:187], v[208:211], v[18:21]
	v_mfma_f32_16x16x32_bf16 v[6:9], v[168:171], v[220:223], v[6:9]
	v_mfma_f32_16x16x32_bf16 v[2:5], v[184:187], v[220:223], v[2:5]
	s_setprio 0
	s_barrier
	s_add_i32 s96, s96, 2
	s_add_u32 s0, s0, 0x100
	s_addc_u32 s1, s1, 0
	s_add_u32 s67, s67, 0x100
	s_addc_u32 s93, s93, 0
	s_cmp_gt_u32 s96, 13
	s_cbranch_scc0 .LBB0_198
	s_and_b64 vcc, exec, s[30:31]
	s_cbranch_vccz .LBB0_201
	s_barrier

.LBB0_772:
	v_add_u32_e32 v3, s35, v164
	ds_read_b128 v[134:137], v3
	ds_read_b128 v[138:141], v3 offset:1024
	ds_read_b128 v[158:161], v3 offset:2048
	ds_read_b128 v[168:171], v3 offset:3072
	v_add_u32_e32 v3, s36, v164
	ds_read_b128 v[172:175], v3
	ds_read_b128 v[176:179], v3 offset:1024
	ds_read_b128 v[180:183], v3 offset:2048
	ds_read_b128 v[184:187], v3 offset:3072
	s_add_u32 s20, s18, 0xfffc0080
	s_addc_u32 s21, s19, -1
	s_cmp_eq_u32 s54, 12
	s_cselect_b32 s45, s11, s21
	s_cselect_b32 s44, s39, s20
	s_cselect_b32 s21, s9, s53
	s_cselect_b32 s20, s51, s52
	v_lshl_add_u64 v[4:5], s[18:19], 0, v[150:151]
	s_add_i32 m0, s25, 0xc000
	ds_read_b128 v[188:191], v166
	ds_read_b128 v[192:195], v166 offset:1024
	ds_read_b128 v[196:199], v166 offset:2048
	ds_read_b128 v[200:203], v166 offset:3072
	ds_read_b128 v[204:207], v166 offset:4096
	ds_read_b128 v[208:211], v166 offset:5120
	ds_read_b128 v[212:215], v166 offset:6144
	ds_read_b128 v[220:223], v166 offset:7168
	global_load_lds_dwordx4 v[4:5], off
	v_lshl_add_u64 v[4:5], s[18:19], 0, v[152:153]
	s_add_i32 m0, s25, 0xe000
	s_nop 0
	global_load_lds_dwordx4 v[4:5], off
	s_waitcnt vmcnt(8)
	s_waitcnt lgkmcnt(0)
	s_barrier
	s_setprio 1
	v_mfma_f32_16x16x32_bf16 v[130:133], v[134:137], v[188:191], v[130:133]
	v_mfma_f32_16x16x32_bf16 v[126:129], v[158:161], v[188:191], v[126:129]
	v_mfma_f32_16x16x32_bf16 v[122:125], v[134:137], v[196:199], v[122:125]
	v_mfma_f32_16x16x32_bf16 v[118:121], v[158:161], v[196:199], v[118:121]
	v_mfma_f32_16x16x32_bf16 v[114:117], v[134:137], v[204:207], v[114:117]
	v_mfma_f32_16x16x32_bf16 v[110:113], v[158:161], v[204:207], v[110:113]
	v_mfma_f32_16x16x32_bf16 v[106:109], v[134:137], v[212:215], v[106:109]
	v_mfma_f32_16x16x32_bf16 v[102:105], v[158:161], v[212:215], v[102:105]
	v_mfma_f32_16x16x32_bf16 v[130:133], v[138:141], v[192:195], v[130:133]
	v_mfma_f32_16x16x32_bf16 v[126:129], v[168:171], v[192:195], v[126:129]
	v_mfma_f32_16x16x32_bf16 v[122:125], v[138:141], v[200:203], v[122:125]
	v_mfma_f32_16x16x32_bf16 v[118:121], v[168:171], v[200:203], v[118:121]
	v_mfma_f32_16x16x32_bf16 v[114:117], v[138:141], v[208:211], v[114:117]
	v_mfma_f32_16x16x32_bf16 v[110:113], v[168:171], v[208:211], v[110:113]
	v_mfma_f32_16x16x32_bf16 v[106:109], v[138:141], v[220:223], v[106:109]
	v_mfma_f32_16x16x32_bf16 v[102:105], v[168:171], v[220:223], v[102:105]
	v_mfma_f32_16x16x32_bf16 v[98:101], v[172:175], v[188:191], v[98:101]
	v_mfma_f32_16x16x32_bf16 v[94:97], v[180:183], v[188:191], v[94:97]
	v_mfma_f32_16x16x32_bf16 v[90:93], v[172:175], v[196:199], v[90:93]
	v_mfma_f32_16x16x32_bf16 v[86:89], v[180:183], v[196:199], v[86:89]
	v_mfma_f32_16x16x32_bf16 v[82:85], v[172:175], v[204:207], v[82:85]
	v_mfma_f32_16x16x32_bf16 v[78:81], v[180:183], v[204:207], v[78:81]
	v_mfma_f32_16x16x32_bf16 v[74:77], v[172:175], v[212:215], v[74:77]
	v_mfma_f32_16x16x32_bf16 v[70:73], v[180:183], v[212:215], v[70:73]
	v_mfma_f32_16x16x32_bf16 v[98:101], v[176:179], v[192:195], v[98:101]
	v_mfma_f32_16x16x32_bf16 v[94:97], v[184:187], v[192:195], v[94:97]
	v_mfma_f32_16x16x32_bf16 v[90:93], v[176:179], v[200:203], v[90:93]
	v_mfma_f32_16x16x32_bf16 v[86:89], v[184:187], v[200:203], v[86:89]
	v_mfma_f32_16x16x32_bf16 v[82:85], v[176:179], v[208:211], v[82:85]
	v_mfma_f32_16x16x32_bf16 v[78:81], v[184:187], v[208:211], v[78:81]
	v_mfma_f32_16x16x32_bf16 v[74:77], v[176:179], v[220:223], v[74:77]
	v_mfma_f32_16x16x32_bf16 v[70:73], v[184:187], v[220:223], v[70:73]
	s_setprio 0
	s_barrier
	s_add_i32 s55, s35, s24
	v_lshl_add_u64 v[162:163], s[20:21], 0, v[146:147]
	s_mov_b32 m0, s55
	ds_read_b128 v[188:191], v166 offset:16384
	ds_read_b128 v[192:195], v166 offset:17408
	ds_read_b128 v[196:199], v166 offset:18432
	ds_read_b128 v[200:203], v166 offset:19456
	ds_read_b128 v[204:207], v166 offset:20480
	ds_read_b128 v[208:211], v166 offset:21504
	ds_read_b128 v[212:215], v166 offset:22528
	ds_read_b128 v[220:223], v166 offset:23552
	global_load_lds_dwordx4 v[162:163], off
	s_add_i32 m0, s55, 0x2000
	s_add_u32 s56, s20, 0x40000
	v_lshl_add_u64 v[216:217], s[20:21], 0, v[142:143]
	s_addc_u32 s57, s21, 0
	s_add_i32 s55, s36, s24
	global_load_lds_dwordx4 v[216:217], off
	v_lshl_add_u64 v[4:5], s[56:57], 0, v[146:147]
	s_mov_b32 m0, s55
	v_lshl_add_u64 v[224:225], s[44:45], 0, v[148:149]
	global_load_lds_dwordx4 v[4:5], off
	v_lshl_add_u64 v[4:5], s[56:57], 0, v[142:143]
	s_add_i32 m0, s55, 0x2000
	v_lshl_add_u64 v[226:227], s[44:45], 0, v[144:145]
	global_load_lds_dwordx4 v[4:5], off
	s_mov_b32 m0, s25
	s_nop 0
	global_load_lds_dwordx4 v[224:225], off
	s_mov_b32 m0, s26
	s_nop 0
	global_load_lds_dwordx4 v[226:227], off
	s_waitcnt vmcnt(8)
	s_waitcnt lgkmcnt(0)
	s_barrier
	s_setprio 1
	v_mfma_f32_16x16x32_bf16 v[66:69], v[134:137], v[188:191], v[66:69]
	v_mfma_f32_16x16x32_bf16 v[62:65], v[158:161], v[188:191], v[62:65]
	v_mfma_f32_16x16x32_bf16 v[58:61], v[134:137], v[196:199], v[58:61]
	v_mfma_f32_16x16x32_bf16 v[54:57], v[158:161], v[196:199], v[54:57]
	v_mfma_f32_16x16x32_bf16 v[50:53], v[134:137], v[204:207], v[50:53]
	v_mfma_f32_16x16x32_bf16 v[46:49], v[158:161], v[204:207], v[46:49]
	v_mfma_f32_16x16x32_bf16 v[42:45], v[134:137], v[212:215], v[42:45]
	v_mfma_f32_16x16x32_bf16 v[38:41], v[158:161], v[212:215], v[38:41]
	v_mfma_f32_16x16x32_bf16 v[66:69], v[138:141], v[192:195], v[66:69]
	v_mfma_f32_16x16x32_bf16 v[62:65], v[168:171], v[192:195], v[62:65]
	v_mfma_f32_16x16x32_bf16 v[58:61], v[138:141], v[200:203], v[58:61]
	v_mfma_f32_16x16x32_bf16 v[54:57], v[168:171], v[200:203], v[54:57]
	v_mfma_f32_16x16x32_bf16 v[50:53], v[138:141], v[208:211], v[50:53]
	v_mfma_f32_16x16x32_bf16 v[46:49], v[168:171], v[208:211], v[46:49]
	v_mfma_f32_16x16x32_bf16 v[42:45], v[138:141], v[220:223], v[42:45]
	v_mfma_f32_16x16x32_bf16 v[38:41], v[168:171], v[220:223], v[38:41]
	v_mfma_f32_16x16x32_bf16 v[34:37], v[172:175], v[188:191], v[34:37]
	v_mfma_f32_16x16x32_bf16 v[30:33], v[180:183], v[188:191], v[30:33]
	v_mfma_f32_16x16x32_bf16 v[26:29], v[172:175], v[196:199], v[26:29]
	v_mfma_f32_16x16x32_bf16 v[22:25], v[180:183], v[196:199], v[22:25]
	v_mfma_f32_16x16x32_bf16 v[18:21], v[172:175], v[204:207], v[18:21]
	v_mfma_f32_16x16x32_bf16 v[14:17], v[180:183], v[204:207], v[14:17]
	v_mfma_f32_16x16x32_bf16 v[10:13], v[172:175], v[212:215], v[10:13]
	v_mfma_f32_16x16x32_bf16 v[4:7], v[180:183], v[212:215], v[6:9]
	v_mfma_f32_16x16x32_bf16 v[34:37], v[176:179], v[192:195], v[34:37]
	v_mfma_f32_16x16x32_bf16 v[30:33], v[184:187], v[192:195], v[30:33]
	v_mfma_f32_16x16x32_bf16 v[26:29], v[176:179], v[200:203], v[26:29]
	v_mfma_f32_16x16x32_bf16 v[22:25], v[184:187], v[200:203], v[22:25]
	v_mfma_f32_16x16x32_bf16 v[18:21], v[176:179], v[208:211], v[18:21]
	v_mfma_f32_16x16x32_bf16 v[14:17], v[184:187], v[208:211], v[14:17]
	v_mfma_f32_16x16x32_bf16 v[10:13], v[176:179], v[220:223], v[10:13]
	v_mfma_f32_16x16x32_bf16 v[4:7], v[184:187], v[220:223], v[4:7]
	s_setprio 0
	s_barrier
	s_add_i32 s55, 0, 0x18000
	v_add_u32_e32 v3, s55, v164
	s_add_i32 s56, 0, 0x1c000
	ds_read_b128 v[134:137], v3
	ds_read_b128 v[138:141], v3 offset:1024
	ds_read_b128 v[158:161], v3 offset:2048
	ds_read_b128 v[168:171], v3 offset:3072
	v_add_u32_e32 v3, s56, v164
	ds_read_b128 v[172:175], v3
	ds_read_b128 v[176:179], v3 offset:1024
	ds_read_b128 v[180:183], v3 offset:2048
	ds_read_b128 v[184:187], v3 offset:3072
	s_add_u32 s44, s44, 0x40000
	s_addc_u32 s45, s45, 0
	s_mov_b32 m0, s27
	v_lshl_add_u64 v[8:9], s[44:45], 0, v[148:149]
	ds_read_b128 v[188:191], v166 offset:32768
	ds_read_b128 v[192:195], v166 offset:33792
	ds_read_b128 v[196:199], v166 offset:34816
	ds_read_b128 v[200:203], v166 offset:35840
	ds_read_b128 v[204:207], v166 offset:36864
	ds_read_b128 v[208:211], v166 offset:37888
	ds_read_b128 v[212:215], v166 offset:38912
	ds_read_b128 v[220:223], v166 offset:39936
	global_load_lds_dwordx4 v[8:9], off
	v_lshl_add_u64 v[8:9], s[44:45], 0, v[144:145]
	s_mov_b32 m0, s28
	s_nop 0
	global_load_lds_dwordx4 v[8:9], off
	s_waitcnt vmcnt(8)
	s_waitcnt lgkmcnt(0)
	s_barrier
	s_setprio 1
	v_mfma_f32_16x16x32_bf16 v[130:133], v[134:137], v[188:191], v[130:133]
	v_mfma_f32_16x16x32_bf16 v[126:129], v[158:161], v[188:191], v[126:129]
	v_mfma_f32_16x16x32_bf16 v[122:125], v[134:137], v[196:199], v[122:125]
	v_mfma_f32_16x16x32_bf16 v[118:121], v[158:161], v[196:199], v[118:121]
	v_mfma_f32_16x16x32_bf16 v[114:117], v[134:137], v[204:207], v[114:117]
	v_mfma_f32_16x16x32_bf16 v[110:113], v[158:161], v[204:207], v[110:113]
	v_mfma_f32_16x16x32_bf16 v[106:109], v[134:137], v[212:215], v[106:109]
	v_mfma_f32_16x16x32_bf16 v[102:105], v[158:161], v[212:215], v[102:105]
	v_mfma_f32_16x16x32_bf16 v[130:133], v[138:141], v[192:195], v[130:133]
	v_mfma_f32_16x16x32_bf16 v[126:129], v[168:171], v[192:195], v[126:129]
	v_mfma_f32_16x16x32_bf16 v[122:125], v[138:141], v[200:203], v[122:125]
	v_mfma_f32_16x16x32_bf16 v[118:121], v[168:171], v[200:203], v[118:121]
	v_mfma_f32_16x16x32_bf16 v[114:117], v[138:141], v[208:211], v[114:117]
	v_mfma_f32_16x16x32_bf16 v[110:113], v[168:171], v[208:211], v[110:113]
	v_mfma_f32_16x16x32_bf16 v[106:109], v[138:141], v[220:223], v[106:109]
	v_mfma_f32_16x16x32_bf16 v[102:105], v[168:171], v[220:223], v[102:105]
	v_mfma_f32_16x16x32_bf16 v[98:101], v[172:175], v[188:191], v[98:101]
	v_mfma_f32_16x16x32_bf16 v[94:97], v[180:183], v[188:191], v[94:97]
	v_mfma_f32_16x16x32_bf16 v[90:93], v[172:175], v[196:199], v[90:93]
	v_mfma_f32_16x16x32_bf16 v[86:89], v[180:183], v[196:199], v[86:89]
	v_mfma_f32_16x16x32_bf16 v[82:85], v[172:175], v[204:207], v[82:85]
	v_mfma_f32_16x16x32_bf16 v[78:81], v[180:183], v[204:207], v[78:81]
	v_mfma_f32_16x16x32_bf16 v[74:77], v[172:175], v[212:215], v[74:77]
	v_mfma_f32_16x16x32_bf16 v[70:73], v[180:183], v[212:215], v[70:73]
	v_mfma_f32_16x16x32_bf16 v[98:101], v[176:179], v[192:195], v[98:101]
	v_mfma_f32_16x16x32_bf16 v[94:97], v[184:187], v[192:195], v[94:97]
	v_mfma_f32_16x16x32_bf16 v[90:93], v[176:179], v[200:203], v[90:93]
	v_mfma_f32_16x16x32_bf16 v[86:89], v[184:187], v[200:203], v[86:89]
	v_mfma_f32_16x16x32_bf16 v[82:85], v[176:179], v[208:211], v[82:85]
	v_mfma_f32_16x16x32_bf16 v[78:81], v[184:187], v[208:211], v[78:81]
	v_mfma_f32_16x16x32_bf16 v[74:77], v[176:179], v[220:223], v[74:77]
	v_mfma_f32_16x16x32_bf16 v[70:73], v[184:187], v[220:223], v[70:73]
	s_setprio 0
	s_barrier
	s_add_i32 s44, s55, s24
	v_lshl_add_u64 v[8:9], v[162:163], 0, s[4:5]
	s_mov_b32 m0, s44
	ds_read_b128 v[188:191], v166 offset:49152
	ds_read_b128 v[192:195], v166 offset:50176
	ds_read_b128 v[196:199], v166 offset:51200
	ds_read_b128 v[200:203], v166 offset:52224
	ds_read_b128 v[204:207], v166 offset:53248
	ds_read_b128 v[208:211], v166 offset:54272
	ds_read_b128 v[212:215], v166 offset:55296
	ds_read_b128 v[220:223], v166 offset:56320
	global_load_lds_dwordx4 v[8:9], off
	s_add_i32 m0, s44, 0x2000
	s_add_u32 s20, s20, 0x40080
	v_lshl_add_u64 v[8:9], v[216:217], 0, s[4:5]
	s_addc_u32 s21, s21, 0
	s_add_i32 s44, s56, s24
	global_load_lds_dwordx4 v[8:9], off
	v_lshl_add_u64 v[8:9], s[20:21], 0, v[146:147]
	s_mov_b32 m0, s44
	s_nop 0
	global_load_lds_dwordx4 v[8:9], off
	v_lshl_add_u64 v[8:9], s[20:21], 0, v[142:143]
	s_add_i32 m0, s44, 0x2000
	s_nop 0
	global_load_lds_dwordx4 v[8:9], off
	v_lshl_add_u64 v[8:9], v[224:225], 0, s[4:5]
	s_mov_b32 m0, s31
	s_nop 0
	global_load_lds_dwordx4 v[8:9], off
	v_lshl_add_u64 v[8:9], v[226:227], 0, s[4:5]
	s_mov_b32 m0, s34
	s_nop 0
	global_load_lds_dwordx4 v[8:9], off
	s_waitcnt vmcnt(8)
	s_waitcnt lgkmcnt(0)
	s_barrier
	s_setprio 1
	v_mfma_f32_16x16x32_bf16 v[66:69], v[134:137], v[188:191], v[66:69]
	v_mfma_f32_16x16x32_bf16 v[62:65], v[158:161], v[188:191], v[62:65]
	v_mfma_f32_16x16x32_bf16 v[58:61], v[134:137], v[196:199], v[58:61]
	v_mfma_f32_16x16x32_bf16 v[54:57], v[158:161], v[196:199], v[54:57]
	v_mfma_f32_16x16x32_bf16 v[50:53], v[134:137], v[204:207], v[50:53]
	v_mfma_f32_16x16x32_bf16 v[46:49], v[158:161], v[204:207], v[46:49]
	v_mfma_f32_16x16x32_bf16 v[42:45], v[134:137], v[212:215], v[42:45]
	v_mfma_f32_16x16x32_bf16 v[38:41], v[158:161], v[212:215], v[38:41]
	v_mfma_f32_16x16x32_bf16 v[66:69], v[138:141], v[192:195], v[66:69]
	v_mfma_f32_16x16x32_bf16 v[62:65], v[168:171], v[192:195], v[62:65]
	v_mfma_f32_16x16x32_bf16 v[58:61], v[138:141], v[200:203], v[58:61]
	v_mfma_f32_16x16x32_bf16 v[54:57], v[168:171], v[200:203], v[54:57]
	v_mfma_f32_16x16x32_bf16 v[50:53], v[138:141], v[208:211], v[50:53]
	v_mfma_f32_16x16x32_bf16 v[46:49], v[168:171], v[208:211], v[46:49]
	v_mfma_f32_16x16x32_bf16 v[42:45], v[138:141], v[220:223], v[42:45]
	v_mfma_f32_16x16x32_bf16 v[38:41], v[168:171], v[220:223], v[38:41]
	v_mfma_f32_16x16x32_bf16 v[34:37], v[172:175], v[188:191], v[34:37]
	v_mfma_f32_16x16x32_bf16 v[30:33], v[180:183], v[188:191], v[30:33]
	v_mfma_f32_16x16x32_bf16 v[26:29], v[172:175], v[196:199], v[26:29]
	v_mfma_f32_16x16x32_bf16 v[22:25], v[180:183], v[196:199], v[22:25]
	v_mfma_f32_16x16x32_bf16 v[18:21], v[172:175], v[204:207], v[18:21]
	v_mfma_f32_16x16x32_bf16 v[14:17], v[180:183], v[204:207], v[14:17]
	v_mfma_f32_16x16x32_bf16 v[8:11], v[172:175], v[212:215], v[10:13]
	v_mfma_f32_16x16x32_bf16 v[4:7], v[180:183], v[212:215], v[4:7]
	v_mfma_f32_16x16x32_bf16 v[34:37], v[176:179], v[192:195], v[34:37]
	v_mfma_f32_16x16x32_bf16 v[30:33], v[184:187], v[192:195], v[30:33]
	v_mfma_f32_16x16x32_bf16 v[26:29], v[176:179], v[200:203], v[26:29]
	v_mfma_f32_16x16x32_bf16 v[22:25], v[184:187], v[200:203], v[22:25]
	v_mfma_f32_16x16x32_bf16 v[18:21], v[176:179], v[208:211], v[18:21]
	v_mfma_f32_16x16x32_bf16 v[14:17], v[184:187], v[208:211], v[14:17]
	v_mfma_f32_16x16x32_bf16 v[10:13], v[176:179], v[220:223], v[8:11]
	v_mfma_f32_16x16x32_bf16 v[6:9], v[184:187], v[220:223], v[4:7]
	s_setprio 0
	s_barrier
	s_add_i32 s54, s54, 2
	s_add_u32 s18, s18, 0x100
	s_addc_u32 s19, s19, 0
	s_add_u32 s52, s52, 0x100
	s_addc_u32 s53, s53, 0
	s_cmp_gt_u32 s54, 13
	s_cbranch_scc0 .LBB0_772
	s_and_b64 vcc, exec, s[6:7]
	s_cbranch_vccz .LBB0_775
	s_barrier

.LBB0_866:
	ds_read_b128 v[34:37], v214
	ds_read_b128 v[46:49], v214 offset:1024
	ds_read_b128 v[54:57], v214 offset:2048
	ds_read_b128 v[62:65], v214 offset:3072
	ds_read_b128 v[150:153], v215
	ds_read_b128 v[154:157], v215 offset:1024
	ds_read_b128 v[158:161], v215 offset:2048
	ds_read_b128 v[162:165], v215 offset:3072
	s_add_u32 s38, s44, 0xfffc0080
	s_addc_u32 s39, s45, -1
	s_cmp_eq_u32 s58, 12
	s_cselect_b32 s55, s5, s39
	s_cselect_b32 s54, s19, s38
	s_cselect_b32 s53, s17, s57
	s_cselect_b32 s52, s37, s56
	v_lshl_add_u64 v[4:5], s[44:45], 0, v[194:195]
	s_add_i32 m0, s25, 0xc000
	ds_read_b128 v[166:169], v216
	ds_read_b128 v[170:173], v216 offset:1024
	ds_read_b128 v[174:177], v216 offset:2048
	ds_read_b128 v[178:181], v216 offset:3072
	ds_read_b128 v[182:185], v216 offset:4096
	ds_read_b128 v[202:205], v216 offset:5120
	ds_read_b128 v[206:209], v216 offset:6144
	ds_read_b128 v[220:223], v216 offset:7168
	global_load_lds_dwordx4 v[4:5], off
	v_lshl_add_u64 v[4:5], s[44:45], 0, v[196:197]
	s_add_i32 m0, s25, 0xe000
	s_nop 0
	global_load_lds_dwordx4 v[4:5], off
	s_waitcnt vmcnt(8)
	s_waitcnt lgkmcnt(0)
	s_barrier
	s_setprio 1
	v_mfma_f32_16x16x32_bf16 v[38:41], v[34:37], v[166:169], v[38:41]
	v_mfma_f32_16x16x32_bf16 v[146:149], v[54:57], v[166:169], v[146:149]
	v_mfma_f32_16x16x32_bf16 v[134:137], v[34:37], v[174:177], v[134:137]
	v_mfma_f32_16x16x32_bf16 v[130:133], v[54:57], v[174:177], v[130:133]
	v_mfma_f32_16x16x32_bf16 v[118:121], v[34:37], v[182:185], v[118:121]
	v_mfma_f32_16x16x32_bf16 v[114:117], v[54:57], v[182:185], v[114:117]
	v_mfma_f32_16x16x32_bf16 v[102:105], v[34:37], v[206:209], v[102:105]
	v_mfma_f32_16x16x32_bf16 v[98:101], v[54:57], v[206:209], v[98:101]
	v_mfma_f32_16x16x32_bf16 v[38:41], v[46:49], v[170:173], v[38:41]
	v_mfma_f32_16x16x32_bf16 v[146:149], v[62:65], v[170:173], v[146:149]
	v_mfma_f32_16x16x32_bf16 v[134:137], v[46:49], v[178:181], v[134:137]
	v_mfma_f32_16x16x32_bf16 v[130:133], v[62:65], v[178:181], v[130:133]
	v_mfma_f32_16x16x32_bf16 v[118:121], v[46:49], v[202:205], v[118:121]
	v_mfma_f32_16x16x32_bf16 v[114:117], v[62:65], v[202:205], v[114:117]
	v_mfma_f32_16x16x32_bf16 v[102:105], v[46:49], v[220:223], v[102:105]
	v_mfma_f32_16x16x32_bf16 v[98:101], v[62:65], v[220:223], v[98:101]
	v_mfma_f32_16x16x32_bf16 v[142:145], v[150:153], v[166:169], v[142:145]
	v_mfma_f32_16x16x32_bf16 v[138:141], v[158:161], v[166:169], v[138:141]
	v_mfma_f32_16x16x32_bf16 v[126:129], v[150:153], v[174:177], v[126:129]
	v_mfma_f32_16x16x32_bf16 v[122:125], v[158:161], v[174:177], v[122:125]
	v_mfma_f32_16x16x32_bf16 v[110:113], v[150:153], v[182:185], v[110:113]
	v_mfma_f32_16x16x32_bf16 v[106:109], v[158:161], v[182:185], v[106:109]
	v_mfma_f32_16x16x32_bf16 v[94:97], v[150:153], v[206:209], v[94:97]
	v_mfma_f32_16x16x32_bf16 v[90:93], v[158:161], v[206:209], v[90:93]
	v_mfma_f32_16x16x32_bf16 v[142:145], v[154:157], v[170:173], v[142:145]
	v_mfma_f32_16x16x32_bf16 v[138:141], v[162:165], v[170:173], v[138:141]
	v_mfma_f32_16x16x32_bf16 v[126:129], v[154:157], v[178:181], v[126:129]
	v_mfma_f32_16x16x32_bf16 v[122:125], v[162:165], v[178:181], v[122:125]
	v_mfma_f32_16x16x32_bf16 v[110:113], v[154:157], v[202:205], v[110:113]
	v_mfma_f32_16x16x32_bf16 v[106:109], v[162:165], v[202:205], v[106:109]
	v_mfma_f32_16x16x32_bf16 v[94:97], v[154:157], v[220:223], v[94:97]
	v_mfma_f32_16x16x32_bf16 v[90:93], v[162:165], v[220:223], v[90:93]
	s_setprio 0
	s_barrier
	s_add_i32 s38, s34, s24
	v_lshl_add_u64 v[210:211], s[52:53], 0, v[186:187]
	s_mov_b32 m0, s38
	ds_read_b128 v[166:169], v216 offset:16384
	ds_read_b128 v[170:173], v216 offset:17408
	ds_read_b128 v[174:177], v216 offset:18432
	ds_read_b128 v[178:181], v216 offset:19456
	ds_read_b128 v[182:185], v216 offset:20480
	ds_read_b128 v[202:205], v216 offset:21504
	ds_read_b128 v[206:209], v216 offset:22528
	ds_read_b128 v[220:223], v216 offset:23552
	global_load_lds_dwordx4 v[210:211], off
	s_add_i32 m0, s38, 0x2000
	s_add_u32 s38, s52, 0x40000
	v_lshl_add_u64 v[224:225], s[52:53], 0, v[188:189]
	s_addc_u32 s39, s53, 0
	s_add_i32 s59, s35, s24
	global_load_lds_dwordx4 v[224:225], off
	v_lshl_add_u64 v[4:5], s[38:39], 0, v[186:187]
	s_mov_b32 m0, s59
	v_lshl_add_u64 v[226:227], s[54:55], 0, v[186:187]
	global_load_lds_dwordx4 v[4:5], off
	v_lshl_add_u64 v[4:5], s[38:39], 0, v[188:189]
	s_add_i32 m0, s59, 0x2000
	v_lshl_add_u64 v[228:229], s[54:55], 0, v[188:189]
	global_load_lds_dwordx4 v[4:5], off
	s_mov_b32 m0, s25
	s_nop 0
	global_load_lds_dwordx4 v[226:227], off
	s_mov_b32 m0, s26
	s_nop 0
	global_load_lds_dwordx4 v[228:229], off
	s_waitcnt vmcnt(8)
	s_waitcnt lgkmcnt(0)
	s_barrier
	s_setprio 1
	v_mfma_f32_16x16x32_bf16 v[86:89], v[34:37], v[166:169], v[86:89]
	v_mfma_f32_16x16x32_bf16 v[82:85], v[54:57], v[166:169], v[82:85]
	v_mfma_f32_16x16x32_bf16 v[70:73], v[34:37], v[174:177], v[70:73]
	v_mfma_f32_16x16x32_bf16 v[66:69], v[54:57], v[174:177], v[66:69]
	v_mfma_f32_16x16x32_bf16 v[42:45], v[34:37], v[182:185], v[42:45]
	v_mfma_f32_16x16x32_bf16 v[30:33], v[54:57], v[182:185], v[30:33]
	v_mfma_f32_16x16x32_bf16 v[18:21], v[34:37], v[206:209], v[18:21]
	v_mfma_f32_16x16x32_bf16 v[14:17], v[54:57], v[206:209], v[14:17]
	v_mfma_f32_16x16x32_bf16 v[86:89], v[46:49], v[170:173], v[86:89]
	v_mfma_f32_16x16x32_bf16 v[82:85], v[62:65], v[170:173], v[82:85]
	v_mfma_f32_16x16x32_bf16 v[70:73], v[46:49], v[178:181], v[70:73]
	v_mfma_f32_16x16x32_bf16 v[66:69], v[62:65], v[178:181], v[66:69]
	v_mfma_f32_16x16x32_bf16 v[42:45], v[46:49], v[202:205], v[42:45]
	v_mfma_f32_16x16x32_bf16 v[30:33], v[62:65], v[202:205], v[30:33]
	v_mfma_f32_16x16x32_bf16 v[18:21], v[46:49], v[220:223], v[18:21]
	v_mfma_f32_16x16x32_bf16 v[14:17], v[62:65], v[220:223], v[14:17]
	v_mfma_f32_16x16x32_bf16 v[50:53], v[158:161], v[174:177], v[50:53]
	v_mfma_f32_16x16x32_bf16 v[26:29], v[150:153], v[182:185], v[26:29]
	v_mfma_f32_16x16x32_bf16 v[22:25], v[158:161], v[182:185], v[22:25]
	v_mfma_f32_16x16x32_bf16 v[10:13], v[150:153], v[206:209], v[10:13]
	v_mfma_f32_16x16x32_bf16 v[4:7], v[158:161], v[206:209], v[6:9]
	v_mfma_f32_16x16x32_bf16 v[34:37], v[150:153], v[166:169], v[78:81]
	v_mfma_f32_16x16x32_bf16 v[46:49], v[158:161], v[166:169], v[74:77]
	v_mfma_f32_16x16x32_bf16 v[54:57], v[150:153], v[174:177], v[58:61]
	v_mfma_f32_16x16x32_bf16 v[50:53], v[162:165], v[178:181], v[50:53]
	v_mfma_f32_16x16x32_bf16 v[26:29], v[154:157], v[202:205], v[26:29]
	v_mfma_f32_16x16x32_bf16 v[22:25], v[162:165], v[202:205], v[22:25]
	v_mfma_f32_16x16x32_bf16 v[10:13], v[154:157], v[220:223], v[10:13]
	v_mfma_f32_16x16x32_bf16 v[4:7], v[162:165], v[220:223], v[4:7]
	v_mfma_f32_16x16x32_bf16 v[34:37], v[154:157], v[170:173], v[34:37]
	v_mfma_f32_16x16x32_bf16 v[46:49], v[162:165], v[170:173], v[46:49]
	v_mfma_f32_16x16x32_bf16 v[54:57], v[154:157], v[178:181], v[54:57]
	s_setprio 0
	s_barrier
	s_add_i32 s59, 0, 0x18000
	v_add_u32_e32 v3, s59, v212
	s_add_i32 s60, 0, 0x1c000
	ds_read_b128 v[58:61], v3
	ds_read_b128 v[62:65], v3 offset:1024
	ds_read_b128 v[74:77], v3 offset:2048
	ds_read_b128 v[78:81], v3 offset:3072
	v_add_u32_e32 v3, s60, v212
	ds_read_b128 v[150:153], v3
	ds_read_b128 v[154:157], v3 offset:1024
	ds_read_b128 v[158:161], v3 offset:2048
	ds_read_b128 v[162:165], v3 offset:3072
	s_add_u32 s38, s54, 0x40000
	s_addc_u32 s39, s55, 0
	s_mov_b32 m0, s27
	v_lshl_add_u64 v[8:9], s[38:39], 0, v[186:187]
	ds_read_b128 v[166:169], v216 offset:32768
	ds_read_b128 v[170:173], v216 offset:33792
	ds_read_b128 v[174:177], v216 offset:34816
	ds_read_b128 v[178:181], v216 offset:35840
	ds_read_b128 v[182:185], v216 offset:36864
	ds_read_b128 v[202:205], v216 offset:37888
	ds_read_b128 v[206:209], v216 offset:38912
	ds_read_b128 v[220:223], v216 offset:39936
	global_load_lds_dwordx4 v[8:9], off
	v_lshl_add_u64 v[8:9], s[38:39], 0, v[188:189]
	s_mov_b32 m0, s28
	s_nop 0
	global_load_lds_dwordx4 v[8:9], off
	s_waitcnt vmcnt(8)
	s_waitcnt lgkmcnt(0)
	s_barrier
	s_setprio 1
	v_mfma_f32_16x16x32_bf16 v[38:41], v[58:61], v[166:169], v[38:41]
	v_mfma_f32_16x16x32_bf16 v[146:149], v[74:77], v[166:169], v[146:149]
	v_mfma_f32_16x16x32_bf16 v[134:137], v[58:61], v[174:177], v[134:137]
	v_mfma_f32_16x16x32_bf16 v[130:133], v[74:77], v[174:177], v[130:133]
	v_mfma_f32_16x16x32_bf16 v[118:121], v[58:61], v[182:185], v[118:121]
	v_mfma_f32_16x16x32_bf16 v[114:117], v[74:77], v[182:185], v[114:117]
	v_mfma_f32_16x16x32_bf16 v[102:105], v[58:61], v[206:209], v[102:105]
	v_mfma_f32_16x16x32_bf16 v[98:101], v[74:77], v[206:209], v[98:101]
	v_mfma_f32_16x16x32_bf16 v[38:41], v[62:65], v[170:173], v[38:41]
	v_mfma_f32_16x16x32_bf16 v[146:149], v[78:81], v[170:173], v[146:149]
	v_mfma_f32_16x16x32_bf16 v[134:137], v[62:65], v[178:181], v[134:137]
	v_mfma_f32_16x16x32_bf16 v[130:133], v[78:81], v[178:181], v[130:133]
	v_mfma_f32_16x16x32_bf16 v[118:121], v[62:65], v[202:205], v[118:121]
	v_mfma_f32_16x16x32_bf16 v[114:117], v[78:81], v[202:205], v[114:117]
	v_mfma_f32_16x16x32_bf16 v[102:105], v[62:65], v[220:223], v[102:105]
	v_mfma_f32_16x16x32_bf16 v[98:101], v[78:81], v[220:223], v[98:101]
	v_mfma_f32_16x16x32_bf16 v[142:145], v[150:153], v[166:169], v[142:145]
	v_mfma_f32_16x16x32_bf16 v[138:141], v[158:161], v[166:169], v[138:141]
	v_mfma_f32_16x16x32_bf16 v[126:129], v[150:153], v[174:177], v[126:129]
	v_mfma_f32_16x16x32_bf16 v[122:125], v[158:161], v[174:177], v[122:125]
	v_mfma_f32_16x16x32_bf16 v[110:113], v[150:153], v[182:185], v[110:113]
	v_mfma_f32_16x16x32_bf16 v[106:109], v[158:161], v[182:185], v[106:109]
	v_mfma_f32_16x16x32_bf16 v[94:97], v[150:153], v[206:209], v[94:97]
	v_mfma_f32_16x16x32_bf16 v[90:93], v[158:161], v[206:209], v[90:93]
	v_mfma_f32_16x16x32_bf16 v[142:145], v[154:157], v[170:173], v[142:145]
	v_mfma_f32_16x16x32_bf16 v[138:141], v[162:165], v[170:173], v[138:141]
	v_mfma_f32_16x16x32_bf16 v[126:129], v[154:157], v[178:181], v[126:129]
	v_mfma_f32_16x16x32_bf16 v[122:125], v[162:165], v[178:181], v[122:125]
	v_mfma_f32_16x16x32_bf16 v[110:113], v[154:157], v[202:205], v[110:113]
	v_mfma_f32_16x16x32_bf16 v[106:109], v[162:165], v[202:205], v[106:109]
	v_mfma_f32_16x16x32_bf16 v[94:97], v[154:157], v[220:223], v[94:97]
	v_mfma_f32_16x16x32_bf16 v[90:93], v[162:165], v[220:223], v[90:93]
	s_setprio 0
	s_barrier
	s_add_i32 s38, s59, s24
	v_lshl_add_u64 v[8:9], v[210:211], 0, s[12:13]
	s_mov_b32 m0, s38
	ds_read_b128 v[166:169], v216 offset:49152
	ds_read_b128 v[170:173], v216 offset:50176
	ds_read_b128 v[174:177], v216 offset:51200
	ds_read_b128 v[178:181], v216 offset:52224
	ds_read_b128 v[182:185], v216 offset:53248
	ds_read_b128 v[202:205], v216 offset:54272
	ds_read_b128 v[206:209], v216 offset:55296
	ds_read_b128 v[220:223], v216 offset:56320
	global_load_lds_dwordx4 v[8:9], off
	s_add_i32 m0, s38, 0x2000
	s_add_u32 s38, s52, 0x40080
	v_lshl_add_u64 v[8:9], v[224:225], 0, s[12:13]
	s_addc_u32 s39, s53, 0
	s_add_i32 s52, s60, s24
	global_load_lds_dwordx4 v[8:9], off
	v_lshl_add_u64 v[8:9], s[38:39], 0, v[186:187]
	s_mov_b32 m0, s52
	s_nop 0
	global_load_lds_dwordx4 v[8:9], off
	v_lshl_add_u64 v[8:9], s[38:39], 0, v[188:189]
	s_add_i32 m0, s52, 0x2000
	s_nop 0
	global_load_lds_dwordx4 v[8:9], off
	v_lshl_add_u64 v[8:9], v[226:227], 0, s[12:13]
	s_mov_b32 m0, s30
	s_nop 0
	global_load_lds_dwordx4 v[8:9], off
	v_lshl_add_u64 v[8:9], v[228:229], 0, s[12:13]
	s_mov_b32 m0, s31
	s_nop 0
	global_load_lds_dwordx4 v[8:9], off
	s_waitcnt vmcnt(8)
	s_waitcnt lgkmcnt(0)
	s_barrier
	s_setprio 1
	v_mfma_f32_16x16x32_bf16 v[86:89], v[58:61], v[166:169], v[86:89]
	v_mfma_f32_16x16x32_bf16 v[82:85], v[74:77], v[166:169], v[82:85]
	v_mfma_f32_16x16x32_bf16 v[70:73], v[58:61], v[174:177], v[70:73]
	v_mfma_f32_16x16x32_bf16 v[66:69], v[74:77], v[174:177], v[66:69]
	v_mfma_f32_16x16x32_bf16 v[42:45], v[58:61], v[182:185], v[42:45]
	v_mfma_f32_16x16x32_bf16 v[30:33], v[74:77], v[182:185], v[30:33]
	v_mfma_f32_16x16x32_bf16 v[18:21], v[58:61], v[206:209], v[18:21]
	v_mfma_f32_16x16x32_bf16 v[14:17], v[74:77], v[206:209], v[14:17]
	v_mfma_f32_16x16x32_bf16 v[86:89], v[62:65], v[170:173], v[86:89]
	v_mfma_f32_16x16x32_bf16 v[82:85], v[78:81], v[170:173], v[82:85]
	v_mfma_f32_16x16x32_bf16 v[70:73], v[62:65], v[178:181], v[70:73]
	v_mfma_f32_16x16x32_bf16 v[66:69], v[78:81], v[178:181], v[66:69]
	v_mfma_f32_16x16x32_bf16 v[42:45], v[62:65], v[202:205], v[42:45]
	v_mfma_f32_16x16x32_bf16 v[30:33], v[78:81], v[202:205], v[30:33]
	v_mfma_f32_16x16x32_bf16 v[18:21], v[62:65], v[220:223], v[18:21]
	v_mfma_f32_16x16x32_bf16 v[14:17], v[78:81], v[220:223], v[14:17]
	v_mfma_f32_16x16x32_bf16 v[34:37], v[150:153], v[166:169], v[34:37]
	v_mfma_f32_16x16x32_bf16 v[78:81], v[154:157], v[170:173], v[34:37]
	v_mfma_f32_16x16x32_bf16 v[34:37], v[158:161], v[166:169], v[46:49]
	v_mfma_f32_16x16x32_bf16 v[74:77], v[162:165], v[170:173], v[34:37]
	v_mfma_f32_16x16x32_bf16 v[34:37], v[150:153], v[174:177], v[54:57]
	v_mfma_f32_16x16x32_bf16 v[58:61], v[154:157], v[178:181], v[34:37]
	v_mfma_f32_16x16x32_bf16 v[34:37], v[158:161], v[174:177], v[50:53]
	v_mfma_f32_16x16x32_bf16 v[26:29], v[150:153], v[182:185], v[26:29]
	v_mfma_f32_16x16x32_bf16 v[22:25], v[158:161], v[182:185], v[22:25]
	v_mfma_f32_16x16x32_bf16 v[8:11], v[150:153], v[206:209], v[10:13]
	v_mfma_f32_16x16x32_bf16 v[4:7], v[158:161], v[206:209], v[4:7]
	v_mfma_f32_16x16x32_bf16 v[50:53], v[162:165], v[178:181], v[34:37]
	v_mfma_f32_16x16x32_bf16 v[26:29], v[154:157], v[202:205], v[26:29]
	v_mfma_f32_16x16x32_bf16 v[22:25], v[162:165], v[202:205], v[22:25]
	v_mfma_f32_16x16x32_bf16 v[10:13], v[154:157], v[220:223], v[8:11]
	v_mfma_f32_16x16x32_bf16 v[6:9], v[162:165], v[220:223], v[4:7]
	s_setprio 0
	s_barrier
	s_add_i32 s58, s58, 2
	s_add_u32 s44, s44, 0x100
	s_addc_u32 s45, s45, 0
	s_add_u32 s56, s56, 0x100
	s_addc_u32 s57, s57, 0
	s_cmp_gt_u32 s58, 13
	s_cbranch_scc0 .LBB0_866
	s_and_b64 vcc, exec, s[14:15]
	s_cbranch_vccz .LBB0_869
	s_barrier

.LBB0_1180:
	ds_read_b128 v[54:57], v238
	ds_read_b128 v[134:137], v238 offset:1024
	ds_read_b128 v[158:161], v238 offset:2048
	ds_read_b128 v[162:165], v238 offset:3072
	ds_read_b128 v[166:169], v239
	ds_read_b128 v[170:173], v239 offset:1024
	ds_read_b128 v[174:177], v239 offset:2048
	ds_read_b128 v[178:181], v239 offset:3072
	s_add_u32 s0, s60, 0x100
	s_addc_u32 s1, s61, 0
	s_cmp_eq_u32 s38, 12
	s_cselect_b32 s65, s19, s1
	s_cselect_b32 s64, s18, s0
	s_cselect_b32 s63, s17, vcc_hi
	s_cselect_b32 s62, s93, vcc_lo
	v_lshl_add_u64 v[214:215], s[60:61], 0, v[150:151]
	s_add_i32 m0, s73, 0xc000
	ds_read_b128 v[182:185], v240
	ds_read_b128 v[186:189], v240 offset:1024
	ds_read_b128 v[190:193], v240 offset:2048
	ds_read_b128 v[194:197], v240 offset:3072
	ds_read_b128 v[198:201], v240 offset:4096
	ds_read_b128 v[202:205], v240 offset:5120
	ds_read_b128 v[206:209], v240 offset:6144
	ds_read_b128 v[210:213], v240 offset:7168
	global_load_lds_dwordx4 v[214:215], off
	v_lshl_add_u64 v[214:215], s[60:61], 0, v[152:153]
	s_add_i32 m0, s73, 0xe000
	s_nop 0
	global_load_lds_dwordx4 v[214:215], off
	s_waitcnt vmcnt(8)
	s_waitcnt lgkmcnt(0)
	s_barrier
	s_setprio 1
	v_mfma_f32_16x16x32_bf16 v[126:129], v[54:57], v[182:185], v[126:129]
	v_mfma_f32_16x16x32_bf16 v[122:125], v[158:161], v[182:185], v[122:125]
	v_mfma_f32_16x16x32_bf16 v[118:121], v[54:57], v[190:193], v[118:121]
	v_mfma_f32_16x16x32_bf16 v[114:117], v[158:161], v[190:193], v[114:117]
	v_mfma_f32_16x16x32_bf16 v[50:53], v[54:57], v[198:201], v[50:53]
	v_mfma_f32_16x16x32_bf16 v[22:25], v[158:161], v[198:201], v[22:25]
	v_mfma_f32_16x16x32_bf16 v[62:65], v[54:57], v[206:209], v[62:65]
	v_mfma_f32_16x16x32_bf16 v[130:133], v[158:161], v[206:209], v[130:133]
	v_mfma_f32_16x16x32_bf16 v[126:129], v[134:137], v[186:189], v[126:129]
	v_mfma_f32_16x16x32_bf16 v[122:125], v[162:165], v[186:189], v[122:125]
	v_mfma_f32_16x16x32_bf16 v[118:121], v[134:137], v[194:197], v[118:121]
	v_mfma_f32_16x16x32_bf16 v[114:117], v[162:165], v[194:197], v[114:117]
	v_mfma_f32_16x16x32_bf16 v[50:53], v[134:137], v[202:205], v[50:53]
	v_mfma_f32_16x16x32_bf16 v[22:25], v[162:165], v[202:205], v[22:25]
	v_mfma_f32_16x16x32_bf16 v[62:65], v[134:137], v[210:213], v[62:65]
	v_mfma_f32_16x16x32_bf16 v[130:133], v[162:165], v[210:213], v[130:133]
	v_mfma_f32_16x16x32_bf16 v[110:113], v[166:169], v[182:185], v[110:113]
	v_mfma_f32_16x16x32_bf16 v[106:109], v[174:177], v[182:185], v[106:109]
	v_mfma_f32_16x16x32_bf16 v[102:105], v[166:169], v[190:193], v[102:105]
	v_mfma_f32_16x16x32_bf16 v[98:101], v[174:177], v[190:193], v[98:101]
	v_mfma_f32_16x16x32_bf16 v[30:33], v[166:169], v[198:201], v[30:33]
	v_mfma_f32_16x16x32_bf16 v[18:21], v[174:177], v[198:201], v[18:21]
	v_mfma_f32_16x16x32_bf16 v[58:61], v[166:169], v[206:209], v[58:61]
	v_mfma_f32_16x16x32_bf16 v[26:29], v[174:177], v[206:209], v[26:29]
	v_mfma_f32_16x16x32_bf16 v[110:113], v[170:173], v[186:189], v[110:113]
	v_mfma_f32_16x16x32_bf16 v[106:109], v[178:181], v[186:189], v[106:109]
	v_mfma_f32_16x16x32_bf16 v[102:105], v[170:173], v[194:197], v[102:105]
	v_mfma_f32_16x16x32_bf16 v[98:101], v[178:181], v[194:197], v[98:101]
	v_mfma_f32_16x16x32_bf16 v[30:33], v[170:173], v[202:205], v[30:33]
	v_mfma_f32_16x16x32_bf16 v[18:21], v[178:181], v[202:205], v[18:21]
	v_mfma_f32_16x16x32_bf16 v[58:61], v[170:173], v[210:213], v[58:61]
	v_mfma_f32_16x16x32_bf16 v[26:29], v[178:181], v[210:213], v[26:29]
	s_setprio 0
	s_barrier
	s_add_i32 s39, s30, s89
	v_lshl_add_u64 v[214:215], s[62:63], 0, v[140:141]
	s_mov_b32 m0, s39
	ds_read_b128 v[182:185], v240 offset:16384
	ds_read_b128 v[186:189], v240 offset:17408
	ds_read_b128 v[190:193], v240 offset:18432
	ds_read_b128 v[194:197], v240 offset:19456
	ds_read_b128 v[198:201], v240 offset:20480
	ds_read_b128 v[202:205], v240 offset:21504
	ds_read_b128 v[206:209], v240 offset:22528
	ds_read_b128 v[210:213], v240 offset:23552
	global_load_lds_dwordx4 v[214:215], off
	s_add_i32 m0, s39, 0x2000
	s_add_u32 s60, s62, 0x40000
	v_lshl_add_u64 v[216:217], s[62:63], 0, v[144:145]
	s_addc_u32 s61, s63, 0
	s_add_i32 s39, s31, s89
	global_load_lds_dwordx4 v[216:217], off
	v_lshl_add_u64 v[244:245], s[60:61], 0, v[140:141]
	s_mov_b32 m0, s39
	v_lshl_add_u64 v[246:247], s[64:65], 0, v[142:143]
	global_load_lds_dwordx4 v[244:245], off
	v_lshl_add_u64 v[244:245], s[60:61], 0, v[144:145]
	s_add_i32 m0, s39, 0x2000
	s_nop 0
	global_load_lds_dwordx4 v[244:245], off
	v_lshl_add_u64 v[244:245], s[64:65], 0, v[138:139]
	s_mov_b32 m0, s73
	s_nop 0
	global_load_lds_dwordx4 v[244:245], off
	s_mov_b32 m0, s24
	s_nop 0
	global_load_lds_dwordx4 v[246:247], off
	s_waitcnt vmcnt(8)
	s_waitcnt lgkmcnt(0)
	s_barrier
	s_setprio 1
	v_mfma_f32_16x16x32_bf16 v[94:97], v[54:57], v[182:185], v[94:97]
	v_mfma_f32_16x16x32_bf16 v[90:93], v[158:161], v[182:185], v[90:93]
	v_mfma_f32_16x16x32_bf16 v[86:89], v[54:57], v[190:193], v[86:89]
	v_mfma_f32_16x16x32_bf16 v[82:85], v[158:161], v[190:193], v[82:85]
	v_mfma_f32_16x16x32_bf16 v[34:37], v[54:57], v[198:201], v[34:37]
	v_mfma_f32_16x16x32_bf16 v[6:9], v[158:161], v[198:201], v[6:9]
	v_mfma_f32_16x16x32_bf16 v[42:45], v[54:57], v[206:209], v[42:45]
	v_mfma_f32_16x16x32_bf16 v[10:13], v[158:161], v[206:209], v[10:13]
	v_mfma_f32_16x16x32_bf16 v[94:97], v[134:137], v[186:189], v[94:97]
	v_mfma_f32_16x16x32_bf16 v[90:93], v[162:165], v[186:189], v[90:93]
	v_mfma_f32_16x16x32_bf16 v[86:89], v[134:137], v[194:197], v[86:89]
	v_mfma_f32_16x16x32_bf16 v[82:85], v[162:165], v[194:197], v[82:85]
	v_mfma_f32_16x16x32_bf16 v[34:37], v[134:137], v[202:205], v[34:37]
	v_mfma_f32_16x16x32_bf16 v[6:9], v[162:165], v[202:205], v[6:9]
	v_mfma_f32_16x16x32_bf16 v[42:45], v[134:137], v[210:213], v[42:45]
	v_mfma_f32_16x16x32_bf16 v[10:13], v[162:165], v[210:213], v[10:13]
	v_mfma_f32_16x16x32_bf16 v[74:77], v[174:177], v[182:185], v[74:77]
	v_mfma_f32_16x16x32_bf16 v[70:73], v[166:169], v[190:193], v[70:73]
	v_mfma_f32_16x16x32_bf16 v[66:69], v[174:177], v[190:193], v[66:69]
	v_mfma_f32_16x16x32_bf16 v[38:41], v[166:169], v[198:201], v[38:41]
	v_mfma_f32_16x16x32_bf16 v[2:5], v[174:177], v[198:201], v[2:5]
	v_mfma_f32_16x16x32_bf16 v[46:49], v[166:169], v[206:209], v[46:49]
	v_mfma_f32_16x16x32_bf16 v[14:17], v[174:177], v[206:209], v[14:17]
	v_mfma_f32_16x16x32_bf16 v[54:57], v[166:169], v[182:185], v[78:81]
	v_mfma_f32_16x16x32_bf16 v[74:77], v[178:181], v[186:189], v[74:77]
	v_mfma_f32_16x16x32_bf16 v[70:73], v[170:173], v[194:197], v[70:73]
	v_mfma_f32_16x16x32_bf16 v[66:69], v[178:181], v[194:197], v[66:69]
	v_mfma_f32_16x16x32_bf16 v[38:41], v[170:173], v[202:205], v[38:41]
	v_mfma_f32_16x16x32_bf16 v[2:5], v[178:181], v[202:205], v[2:5]
	v_mfma_f32_16x16x32_bf16 v[46:49], v[170:173], v[210:213], v[46:49]
	v_mfma_f32_16x16x32_bf16 v[14:17], v[178:181], v[210:213], v[14:17]
	v_mfma_f32_16x16x32_bf16 v[54:57], v[170:173], v[186:189], v[54:57]
	s_setprio 0
	s_barrier
	s_add_i32 s39, 0, 0x18000
	v_add_u32_e32 v146, s39, v1
	s_add_i32 s94, 0, 0x1c000
	ds_read_b128 v[78:81], v146
	ds_read_b128 v[134:137], v146 offset:1024
	ds_read_b128 v[158:161], v146 offset:2048
	ds_read_b128 v[162:165], v146 offset:3072
	v_add_u32_e32 v146, s94, v1
	ds_read_b128 v[166:169], v146
	ds_read_b128 v[170:173], v146 offset:1024
	ds_read_b128 v[174:177], v146 offset:2048
	ds_read_b128 v[178:181], v146 offset:3072
	s_add_u32 s60, s64, 0x40000
	s_addc_u32 s61, s65, 0
	s_mov_b32 m0, s25
	v_lshl_add_u64 v[248:249], s[60:61], 0, v[138:139]
	ds_read_b128 v[182:185], v240 offset:32768
	ds_read_b128 v[186:189], v240 offset:33792
	ds_read_b128 v[190:193], v240 offset:34816
	ds_read_b128 v[194:197], v240 offset:35840
	ds_read_b128 v[198:201], v240 offset:36864
	ds_read_b128 v[202:205], v240 offset:37888
	ds_read_b128 v[206:209], v240 offset:38912
	ds_read_b128 v[210:213], v240 offset:39936
	global_load_lds_dwordx4 v[248:249], off
	v_lshl_add_u64 v[248:249], s[60:61], 0, v[142:143]
	s_mov_b32 m0, s26
	s_nop 0
	global_load_lds_dwordx4 v[248:249], off
	s_waitcnt vmcnt(8)
	s_waitcnt lgkmcnt(0)
	s_barrier
	s_setprio 1
	v_mfma_f32_16x16x32_bf16 v[126:129], v[78:81], v[182:185], v[126:129]
	v_mfma_f32_16x16x32_bf16 v[122:125], v[158:161], v[182:185], v[122:125]
	v_mfma_f32_16x16x32_bf16 v[118:121], v[78:81], v[190:193], v[118:121]
	v_mfma_f32_16x16x32_bf16 v[114:117], v[158:161], v[190:193], v[114:117]
	v_mfma_f32_16x16x32_bf16 v[50:53], v[78:81], v[198:201], v[50:53]
	v_mfma_f32_16x16x32_bf16 v[22:25], v[158:161], v[198:201], v[22:25]
	v_mfma_f32_16x16x32_bf16 v[62:65], v[78:81], v[206:209], v[62:65]
	v_mfma_f32_16x16x32_bf16 v[130:133], v[158:161], v[206:209], v[130:133]
	v_mfma_f32_16x16x32_bf16 v[126:129], v[134:137], v[186:189], v[126:129]
	v_mfma_f32_16x16x32_bf16 v[122:125], v[162:165], v[186:189], v[122:125]
	v_mfma_f32_16x16x32_bf16 v[118:121], v[134:137], v[194:197], v[118:121]
	v_mfma_f32_16x16x32_bf16 v[114:117], v[162:165], v[194:197], v[114:117]
	v_mfma_f32_16x16x32_bf16 v[50:53], v[134:137], v[202:205], v[50:53]
	v_mfma_f32_16x16x32_bf16 v[22:25], v[162:165], v[202:205], v[22:25]
	v_mfma_f32_16x16x32_bf16 v[62:65], v[134:137], v[210:213], v[62:65]
	v_mfma_f32_16x16x32_bf16 v[130:133], v[162:165], v[210:213], v[130:133]
	v_mfma_f32_16x16x32_bf16 v[110:113], v[166:169], v[182:185], v[110:113]
	v_mfma_f32_16x16x32_bf16 v[106:109], v[174:177], v[182:185], v[106:109]
	v_mfma_f32_16x16x32_bf16 v[102:105], v[166:169], v[190:193], v[102:105]
	v_mfma_f32_16x16x32_bf16 v[98:101], v[174:177], v[190:193], v[98:101]
	v_mfma_f32_16x16x32_bf16 v[30:33], v[166:169], v[198:201], v[30:33]
	v_mfma_f32_16x16x32_bf16 v[18:21], v[174:177], v[198:201], v[18:21]
	v_mfma_f32_16x16x32_bf16 v[58:61], v[166:169], v[206:209], v[58:61]
	v_mfma_f32_16x16x32_bf16 v[26:29], v[174:177], v[206:209], v[26:29]
	v_mfma_f32_16x16x32_bf16 v[110:113], v[170:173], v[186:189], v[110:113]
	v_mfma_f32_16x16x32_bf16 v[106:109], v[178:181], v[186:189], v[106:109]
	v_mfma_f32_16x16x32_bf16 v[102:105], v[170:173], v[194:197], v[102:105]
	v_mfma_f32_16x16x32_bf16 v[98:101], v[178:181], v[194:197], v[98:101]
	v_mfma_f32_16x16x32_bf16 v[30:33], v[170:173], v[202:205], v[30:33]
	v_mfma_f32_16x16x32_bf16 v[18:21], v[178:181], v[202:205], v[18:21]
	v_mfma_f32_16x16x32_bf16 v[58:61], v[170:173], v[210:213], v[58:61]
	v_mfma_f32_16x16x32_bf16 v[26:29], v[178:181], v[210:213], v[26:29]
	s_setprio 0
	s_barrier
	s_add_i32 s39, s39, s89
	v_lshl_add_u64 v[214:215], v[214:215], 0, s[76:77]
	s_mov_b32 m0, s39
	ds_read_b128 v[182:185], v240 offset:49152
	ds_read_b128 v[186:189], v240 offset:50176
	ds_read_b128 v[190:193], v240 offset:51200
	ds_read_b128 v[194:197], v240 offset:52224
	ds_read_b128 v[198:201], v240 offset:53248
	ds_read_b128 v[202:205], v240 offset:54272
	ds_read_b128 v[206:209], v240 offset:55296
	ds_read_b128 v[210:213], v240 offset:56320
	global_load_lds_dwordx4 v[214:215], off
	s_add_i32 m0, s39, 0x2000
	s_add_u32 s60, s62, 0x40080
	v_lshl_add_u64 v[214:215], v[216:217], 0, s[76:77]
	s_addc_u32 s61, s63, 0
	s_add_i32 s39, s94, s89
	global_load_lds_dwordx4 v[214:215], off
	v_lshl_add_u64 v[214:215], s[60:61], 0, v[140:141]
	s_mov_b32 m0, s39
	s_nop 0
	global_load_lds_dwordx4 v[214:215], off
	v_lshl_add_u64 v[214:215], s[60:61], 0, v[144:145]
	s_add_i32 m0, s39, 0x2000
	s_nop 0
	global_load_lds_dwordx4 v[214:215], off
	v_lshl_add_u64 v[214:215], v[244:245], 0, s[76:77]
	s_mov_b32 m0, s27
	s_nop 0
	global_load_lds_dwordx4 v[214:215], off
	v_lshl_add_u64 v[214:215], v[246:247], 0, s[76:77]
	s_mov_b32 m0, s28
	s_nop 0
	global_load_lds_dwordx4 v[214:215], off
	s_waitcnt vmcnt(8)
	s_waitcnt lgkmcnt(0)
	s_barrier
	s_setprio 1
	v_mfma_f32_16x16x32_bf16 v[94:97], v[78:81], v[182:185], v[94:97]
	v_mfma_f32_16x16x32_bf16 v[90:93], v[158:161], v[182:185], v[90:93]
	v_mfma_f32_16x16x32_bf16 v[86:89], v[78:81], v[190:193], v[86:89]
	v_mfma_f32_16x16x32_bf16 v[82:85], v[158:161], v[190:193], v[82:85]
	v_mfma_f32_16x16x32_bf16 v[34:37], v[78:81], v[198:201], v[34:37]
	v_mfma_f32_16x16x32_bf16 v[6:9], v[158:161], v[198:201], v[6:9]
	v_mfma_f32_16x16x32_bf16 v[42:45], v[78:81], v[206:209], v[42:45]
	v_mfma_f32_16x16x32_bf16 v[10:13], v[158:161], v[206:209], v[10:13]
	v_mfma_f32_16x16x32_bf16 v[94:97], v[134:137], v[186:189], v[94:97]
	v_mfma_f32_16x16x32_bf16 v[90:93], v[162:165], v[186:189], v[90:93]
	v_mfma_f32_16x16x32_bf16 v[86:89], v[134:137], v[194:197], v[86:89]
	v_mfma_f32_16x16x32_bf16 v[82:85], v[162:165], v[194:197], v[82:85]
	v_mfma_f32_16x16x32_bf16 v[34:37], v[134:137], v[202:205], v[34:37]
	v_mfma_f32_16x16x32_bf16 v[6:9], v[162:165], v[202:205], v[6:9]
	v_mfma_f32_16x16x32_bf16 v[42:45], v[134:137], v[210:213], v[42:45]
	v_mfma_f32_16x16x32_bf16 v[10:13], v[162:165], v[210:213], v[10:13]
	v_mfma_f32_16x16x32_bf16 v[54:57], v[166:169], v[182:185], v[54:57]
	v_mfma_f32_16x16x32_bf16 v[78:81], v[170:173], v[186:189], v[54:57]
	v_mfma_f32_16x16x32_bf16 v[54:57], v[174:177], v[182:185], v[74:77]
	v_mfma_f32_16x16x32_bf16 v[74:77], v[178:181], v[186:189], v[54:57]
	v_mfma_f32_16x16x32_bf16 v[54:57], v[166:169], v[190:193], v[70:73]
	v_mfma_f32_16x16x32_bf16 v[70:73], v[170:173], v[194:197], v[54:57]
	v_mfma_f32_16x16x32_bf16 v[54:57], v[174:177], v[190:193], v[66:69]
	v_mfma_f32_16x16x32_bf16 v[38:41], v[166:169], v[198:201], v[38:41]
	v_mfma_f32_16x16x32_bf16 v[2:5], v[174:177], v[198:201], v[2:5]
	v_mfma_f32_16x16x32_bf16 v[46:49], v[166:169], v[206:209], v[46:49]
	v_mfma_f32_16x16x32_bf16 v[14:17], v[174:177], v[206:209], v[14:17]
	v_mfma_f32_16x16x32_bf16 v[66:69], v[178:181], v[194:197], v[54:57]
	v_mfma_f32_16x16x32_bf16 v[38:41], v[170:173], v[202:205], v[38:41]
	v_mfma_f32_16x16x32_bf16 v[2:5], v[178:181], v[202:205], v[2:5]
	v_mfma_f32_16x16x32_bf16 v[46:49], v[170:173], v[210:213], v[46:49]
	v_mfma_f32_16x16x32_bf16 v[14:17], v[178:181], v[210:213], v[14:17]
	s_setprio 0
	s_barrier
	s_add_i32 s38, s38, 2
	s_add_u32 vcc_lo, vcc_lo, 0x100
	s_addc_u32 vcc_hi, vcc_hi, 0
	s_cmp_gt_u32 s38, 13
	s_mov_b64 s[60:61], s[0:1]
	s_cbranch_scc0 .LBB0_1180
	v_readfirstlane_b32 s98, v218
	s_nop 1
	s_lshr_b32 s98, s98, 6
	s_cmp_gt_u32 s98, 3
	s_cbranch_scc1 .Lr_stage_done
	s_mul_i32 s99, s37, 0xfe
	s_add_i32 s99, s99, -2
	s_ashr_i32 s99, s99, 12
	s_mul_i32 s99, s99, 0x5800
	s_add_i32 s99, s99, 0x2c000
	s_add_u32 s100, s68, s99
	s_addc_u32 s101, s69, 0
	s_cmp_eq_u32 s98, 0
	s_cselect_b32 s100, s4, s100
	s_cselect_b32 s101, s5, s101
	s_cmp_eq_u32 s98, 1
	s_cselect_b32 s100, s96, s100
	s_cselect_b32 s101, s97, s101
	s_cmp_eq_u32 s98, 2
	s_cselect_b32 s100, s78, s100
	s_cselect_b32 s101, s79, s101
	s_lshl_b32 s99, s72, 10
	s_add_u32 s100, s100, s99
	s_addc_u32 s101, s101, 0
	s_lshl_b32 s98, s98, 10
	s_add_i32 m0, s98, 0x24000
	v_and_b32_e32 v248, 63, v218
	v_lshlrev_b32_e32 v248, 4, v248
	s_nop 0
	global_load_lds_dwordx4 v248, s[100:101]

.LBB0_1341:
	ds_read_b128 v[42:45], v166
	ds_read_b128 v[54:57], v166 offset:1024
	ds_read_b128 v[58:61], v166 offset:2048
	ds_read_b128 v[62:65], v166 offset:3072
	ds_read_b128 v[158:161], v167
	ds_read_b128 v[170:173], v167 offset:1024
	ds_read_b128 v[174:177], v167 offset:2048
	ds_read_b128 v[178:181], v167 offset:3072
	s_add_u32 s18, s16, 0x100
	s_addc_u32 s19, s17, 0
	s_cmp_eq_u32 s38, 40
	s_cselect_b32 s45, s1, s19
	s_cselect_b32 s44, s0, s18
	s_cselect_b32 s21, s15, s49
	s_cselect_b32 s20, s14, s48
	v_lshl_add_u64 v[162:163], s[16:17], 0, v[150:151]
	s_add_i32 m0, s24, 0xc000
	ds_read_b128 v[182:185], v168
	ds_read_b128 v[186:189], v168 offset:1024
	ds_read_b128 v[190:193], v168 offset:2048
	ds_read_b128 v[194:197], v168 offset:3072
	ds_read_b128 v[198:201], v168 offset:4096
	ds_read_b128 v[202:205], v168 offset:5120
	ds_read_b128 v[206:209], v168 offset:6144
	ds_read_b128 v[210:213], v168 offset:7168
	global_load_lds_dwordx4 v[162:163], off
	v_lshl_add_u64 v[162:163], s[16:17], 0, v[152:153]
	s_add_i32 m0, s24, 0xe000
	s_nop 0
	global_load_lds_dwordx4 v[162:163], off
	s_waitcnt vmcnt(8)
	s_waitcnt lgkmcnt(0)
	s_barrier
	s_setprio 1
	v_mfma_f32_16x16x32_bf16 v[142:145], v[42:45], v[182:185], v[142:145]
	v_mfma_f32_16x16x32_bf16 v[138:141], v[58:61], v[182:185], v[138:141]
	v_mfma_f32_16x16x32_bf16 v[126:129], v[42:45], v[190:193], v[126:129]
	v_mfma_f32_16x16x32_bf16 v[122:125], v[58:61], v[190:193], v[122:125]
	v_mfma_f32_16x16x32_bf16 v[110:113], v[42:45], v[198:201], v[110:113]
	v_mfma_f32_16x16x32_bf16 v[106:109], v[58:61], v[198:201], v[106:109]
	v_mfma_f32_16x16x32_bf16 v[94:97], v[42:45], v[206:209], v[94:97]
	v_mfma_f32_16x16x32_bf16 v[90:93], v[58:61], v[206:209], v[90:93]
	v_mfma_f32_16x16x32_bf16 v[142:145], v[54:57], v[186:189], v[142:145]
	v_mfma_f32_16x16x32_bf16 v[138:141], v[62:65], v[186:189], v[138:141]
	v_mfma_f32_16x16x32_bf16 v[126:129], v[54:57], v[194:197], v[126:129]
	v_mfma_f32_16x16x32_bf16 v[122:125], v[62:65], v[194:197], v[122:125]
	v_mfma_f32_16x16x32_bf16 v[110:113], v[54:57], v[202:205], v[110:113]
	v_mfma_f32_16x16x32_bf16 v[106:109], v[62:65], v[202:205], v[106:109]
	v_mfma_f32_16x16x32_bf16 v[94:97], v[54:57], v[210:213], v[94:97]
	v_mfma_f32_16x16x32_bf16 v[90:93], v[62:65], v[210:213], v[90:93]
	v_mfma_f32_16x16x32_bf16 v[134:137], v[158:161], v[182:185], v[134:137]
	v_mfma_f32_16x16x32_bf16 v[130:133], v[174:177], v[182:185], v[130:133]
	v_mfma_f32_16x16x32_bf16 v[118:121], v[158:161], v[190:193], v[118:121]
	v_mfma_f32_16x16x32_bf16 v[114:117], v[174:177], v[190:193], v[114:117]
	v_mfma_f32_16x16x32_bf16 v[102:105], v[158:161], v[198:201], v[102:105]
	v_mfma_f32_16x16x32_bf16 v[98:101], v[174:177], v[198:201], v[98:101]
	v_mfma_f32_16x16x32_bf16 v[86:89], v[158:161], v[206:209], v[86:89]
	v_mfma_f32_16x16x32_bf16 v[82:85], v[174:177], v[206:209], v[82:85]
	v_mfma_f32_16x16x32_bf16 v[134:137], v[170:173], v[186:189], v[134:137]
	v_mfma_f32_16x16x32_bf16 v[130:133], v[178:181], v[186:189], v[130:133]
	v_mfma_f32_16x16x32_bf16 v[118:121], v[170:173], v[194:197], v[118:121]
	v_mfma_f32_16x16x32_bf16 v[114:117], v[178:181], v[194:197], v[114:117]
	v_mfma_f32_16x16x32_bf16 v[102:105], v[170:173], v[202:205], v[102:105]
	v_mfma_f32_16x16x32_bf16 v[98:101], v[178:181], v[202:205], v[98:101]
	v_mfma_f32_16x16x32_bf16 v[86:89], v[170:173], v[210:213], v[86:89]
	v_mfma_f32_16x16x32_bf16 v[82:85], v[178:181], v[210:213], v[82:85]
	s_setprio 0
	s_barrier
	s_add_i32 s16, s35, s23
	v_lshl_add_u64 v[162:163], s[20:21], 0, v[146:147]
	s_mov_b32 m0, s16
	ds_read_b128 v[182:185], v168 offset:16384
	ds_read_b128 v[186:189], v168 offset:17408
	ds_read_b128 v[190:193], v168 offset:18432
	ds_read_b128 v[194:197], v168 offset:19456
	ds_read_b128 v[198:201], v168 offset:20480
	ds_read_b128 v[202:205], v168 offset:21504
	ds_read_b128 v[206:209], v168 offset:22528
	ds_read_b128 v[210:213], v168 offset:23552
	global_load_lds_dwordx4 v[162:163], off
	s_add_i32 m0, s16, 0x2000
	s_add_u32 s16, s20, 0xb0000
	v_lshl_add_u64 v[214:215], s[20:21], 0, v[148:149]
	s_addc_u32 s17, s21, 0
	s_add_i32 s39, s36, s23
	global_load_lds_dwordx4 v[214:215], off
	v_lshl_add_u64 v[216:217], s[16:17], 0, v[146:147]
	s_mov_b32 m0, s39
	v_lshl_add_u64 v[220:221], s[44:45], 0, v[148:149]
	global_load_lds_dwordx4 v[216:217], off
	v_lshl_add_u64 v[216:217], s[16:17], 0, v[148:149]
	s_add_i32 m0, s39, 0x2000
	s_nop 0
	global_load_lds_dwordx4 v[216:217], off
	v_lshl_add_u64 v[216:217], s[44:45], 0, v[146:147]
	s_mov_b32 m0, s24
	s_nop 0
	global_load_lds_dwordx4 v[216:217], off
	s_mov_b32 m0, s25
	s_nop 0
	global_load_lds_dwordx4 v[220:221], off
	s_waitcnt vmcnt(8)
	s_waitcnt lgkmcnt(0)
	s_barrier
	s_setprio 1
	v_mfma_f32_16x16x32_bf16 v[78:81], v[42:45], v[182:185], v[78:81]
	v_mfma_f32_16x16x32_bf16 v[74:77], v[58:61], v[182:185], v[74:77]
	v_mfma_f32_16x16x32_bf16 v[50:53], v[42:45], v[190:193], v[50:53]
	v_mfma_f32_16x16x32_bf16 v[46:49], v[58:61], v[190:193], v[46:49]
	v_mfma_f32_16x16x32_bf16 v[30:33], v[42:45], v[198:201], v[30:33]
	v_mfma_f32_16x16x32_bf16 v[26:29], v[58:61], v[198:201], v[26:29]
	v_mfma_f32_16x16x32_bf16 v[14:17], v[42:45], v[206:209], v[14:17]
	v_mfma_f32_16x16x32_bf16 v[10:13], v[58:61], v[206:209], v[10:13]
	v_mfma_f32_16x16x32_bf16 v[78:81], v[54:57], v[186:189], v[78:81]
	v_mfma_f32_16x16x32_bf16 v[74:77], v[62:65], v[186:189], v[74:77]
	v_mfma_f32_16x16x32_bf16 v[50:53], v[54:57], v[194:197], v[50:53]
	v_mfma_f32_16x16x32_bf16 v[46:49], v[62:65], v[194:197], v[46:49]
	v_mfma_f32_16x16x32_bf16 v[30:33], v[54:57], v[202:205], v[30:33]
	v_mfma_f32_16x16x32_bf16 v[26:29], v[62:65], v[202:205], v[26:29]
	v_mfma_f32_16x16x32_bf16 v[14:17], v[54:57], v[210:213], v[14:17]
	v_mfma_f32_16x16x32_bf16 v[10:13], v[62:65], v[210:213], v[10:13]
	v_mfma_f32_16x16x32_bf16 v[38:41], v[158:161], v[190:193], v[38:41]
	v_mfma_f32_16x16x32_bf16 v[34:37], v[174:177], v[190:193], v[34:37]
	v_mfma_f32_16x16x32_bf16 v[22:25], v[158:161], v[198:201], v[22:25]
	v_mfma_f32_16x16x32_bf16 v[18:21], v[174:177], v[198:201], v[18:21]
	v_mfma_f32_16x16x32_bf16 v[6:9], v[158:161], v[206:209], v[6:9]
	v_mfma_f32_16x16x32_bf16 v[2:5], v[174:177], v[206:209], v[2:5]
	v_mfma_f32_16x16x32_bf16 v[42:45], v[158:161], v[182:185], v[70:73]
	v_mfma_f32_16x16x32_bf16 v[54:57], v[174:177], v[182:185], v[66:69]
	v_mfma_f32_16x16x32_bf16 v[38:41], v[170:173], v[194:197], v[38:41]
	v_mfma_f32_16x16x32_bf16 v[34:37], v[178:181], v[194:197], v[34:37]
	v_mfma_f32_16x16x32_bf16 v[22:25], v[170:173], v[202:205], v[22:25]
	v_mfma_f32_16x16x32_bf16 v[18:21], v[178:181], v[202:205], v[18:21]
	v_mfma_f32_16x16x32_bf16 v[6:9], v[170:173], v[210:213], v[6:9]
	v_mfma_f32_16x16x32_bf16 v[2:5], v[178:181], v[210:213], v[2:5]
	v_mfma_f32_16x16x32_bf16 v[42:45], v[170:173], v[186:189], v[42:45]
	v_mfma_f32_16x16x32_bf16 v[54:57], v[178:181], v[186:189], v[54:57]
	s_setprio 0
	s_barrier
	s_add_i32 s39, 0, 0x18000
	s_add_i32 s50, 0, 0x1c000
	v_add_u32_e32 v70, s39, v164
	v_add_u32_e32 v178, s50, v164
	ds_read_b128 v[58:61], v70
	ds_read_b128 v[62:65], v70 offset:1024
	ds_read_b128 v[66:69], v70 offset:2048
	ds_read_b128 v[70:73], v70 offset:3072
	ds_read_b128 v[158:161], v178
	ds_read_b128 v[170:173], v178 offset:1024
	ds_read_b128 v[174:177], v178 offset:2048
	ds_read_b128 v[178:181], v178 offset:3072
	s_add_u32 s16, s44, 0xb0000
	s_addc_u32 s17, s45, 0
	s_mov_b32 m0, s26
	v_lshl_add_u64 v[222:223], s[16:17], 0, v[146:147]
	ds_read_b128 v[182:185], v168 offset:32768
	ds_read_b128 v[186:189], v168 offset:33792
	ds_read_b128 v[190:193], v168 offset:34816
	ds_read_b128 v[194:197], v168 offset:35840
	ds_read_b128 v[198:201], v168 offset:36864
	ds_read_b128 v[202:205], v168 offset:37888
	ds_read_b128 v[206:209], v168 offset:38912
	ds_read_b128 v[210:213], v168 offset:39936
	global_load_lds_dwordx4 v[222:223], off
	v_lshl_add_u64 v[222:223], s[16:17], 0, v[148:149]
	s_mov_b32 m0, s27
	s_nop 0
	global_load_lds_dwordx4 v[222:223], off
	s_waitcnt vmcnt(8)
	s_waitcnt lgkmcnt(0)
	s_barrier
	s_setprio 1
	v_mfma_f32_16x16x32_bf16 v[142:145], v[58:61], v[182:185], v[142:145]
	v_mfma_f32_16x16x32_bf16 v[138:141], v[66:69], v[182:185], v[138:141]
	v_mfma_f32_16x16x32_bf16 v[126:129], v[58:61], v[190:193], v[126:129]
	v_mfma_f32_16x16x32_bf16 v[122:125], v[66:69], v[190:193], v[122:125]
	v_mfma_f32_16x16x32_bf16 v[110:113], v[58:61], v[198:201], v[110:113]
	v_mfma_f32_16x16x32_bf16 v[106:109], v[66:69], v[198:201], v[106:109]
	v_mfma_f32_16x16x32_bf16 v[94:97], v[58:61], v[206:209], v[94:97]
	v_mfma_f32_16x16x32_bf16 v[90:93], v[66:69], v[206:209], v[90:93]
	v_mfma_f32_16x16x32_bf16 v[142:145], v[62:65], v[186:189], v[142:145]
	v_mfma_f32_16x16x32_bf16 v[138:141], v[70:73], v[186:189], v[138:141]
	v_mfma_f32_16x16x32_bf16 v[126:129], v[62:65], v[194:197], v[126:129]
	v_mfma_f32_16x16x32_bf16 v[122:125], v[70:73], v[194:197], v[122:125]
	v_mfma_f32_16x16x32_bf16 v[110:113], v[62:65], v[202:205], v[110:113]
	v_mfma_f32_16x16x32_bf16 v[106:109], v[70:73], v[202:205], v[106:109]
	v_mfma_f32_16x16x32_bf16 v[94:97], v[62:65], v[210:213], v[94:97]
	v_mfma_f32_16x16x32_bf16 v[90:93], v[70:73], v[210:213], v[90:93]
	v_mfma_f32_16x16x32_bf16 v[134:137], v[158:161], v[182:185], v[134:137]
	v_mfma_f32_16x16x32_bf16 v[130:133], v[174:177], v[182:185], v[130:133]
	v_mfma_f32_16x16x32_bf16 v[118:121], v[158:161], v[190:193], v[118:121]
	v_mfma_f32_16x16x32_bf16 v[114:117], v[174:177], v[190:193], v[114:117]
	v_mfma_f32_16x16x32_bf16 v[102:105], v[158:161], v[198:201], v[102:105]
	v_mfma_f32_16x16x32_bf16 v[98:101], v[174:177], v[198:201], v[98:101]
	v_mfma_f32_16x16x32_bf16 v[86:89], v[158:161], v[206:209], v[86:89]
	v_mfma_f32_16x16x32_bf16 v[82:85], v[174:177], v[206:209], v[82:85]
	v_mfma_f32_16x16x32_bf16 v[134:137], v[170:173], v[186:189], v[134:137]
	v_mfma_f32_16x16x32_bf16 v[130:133], v[178:181], v[186:189], v[130:133]
	v_mfma_f32_16x16x32_bf16 v[118:121], v[170:173], v[194:197], v[118:121]
	v_mfma_f32_16x16x32_bf16 v[114:117], v[178:181], v[194:197], v[114:117]
	v_mfma_f32_16x16x32_bf16 v[102:105], v[170:173], v[202:205], v[102:105]
	v_mfma_f32_16x16x32_bf16 v[98:101], v[178:181], v[202:205], v[98:101]
	v_mfma_f32_16x16x32_bf16 v[86:89], v[170:173], v[210:213], v[86:89]
	v_mfma_f32_16x16x32_bf16 v[82:85], v[178:181], v[210:213], v[82:85]
	s_setprio 0
	s_barrier
	s_add_i32 s16, s39, s23
	v_lshl_add_u64 v[162:163], v[162:163], 0, s[10:11]
	s_mov_b32 m0, s16
	ds_read_b128 v[182:185], v168 offset:49152
	ds_read_b128 v[186:189], v168 offset:50176
	ds_read_b128 v[190:193], v168 offset:51200
	ds_read_b128 v[194:197], v168 offset:52224
	ds_read_b128 v[198:201], v168 offset:53248
	ds_read_b128 v[202:205], v168 offset:54272
	ds_read_b128 v[206:209], v168 offset:55296
	ds_read_b128 v[210:213], v168 offset:56320
	global_load_lds_dwordx4 v[162:163], off
	s_add_i32 m0, s16, 0x2000
	s_add_u32 s16, s20, 0xb0080
	v_lshl_add_u64 v[162:163], v[214:215], 0, s[10:11]
	s_addc_u32 s17, s21, 0
	s_add_i32 s20, s50, s23
	global_load_lds_dwordx4 v[162:163], off
	v_lshl_add_u64 v[162:163], s[16:17], 0, v[146:147]
	s_mov_b32 m0, s20
	s_nop 0
	global_load_lds_dwordx4 v[162:163], off
	v_lshl_add_u64 v[162:163], s[16:17], 0, v[148:149]
	s_add_i32 m0, s20, 0x2000
	s_nop 0
	global_load_lds_dwordx4 v[162:163], off
	v_lshl_add_u64 v[162:163], v[216:217], 0, s[10:11]
	s_mov_b32 m0, s29
	s_nop 0
	global_load_lds_dwordx4 v[162:163], off
	v_lshl_add_u64 v[162:163], v[220:221], 0, s[10:11]
	s_mov_b32 m0, s34
	s_nop 0
	global_load_lds_dwordx4 v[162:163], off
	s_waitcnt vmcnt(8)
	s_waitcnt lgkmcnt(0)
	s_barrier
	s_setprio 1
	v_mfma_f32_16x16x32_bf16 v[78:81], v[58:61], v[182:185], v[78:81]
	v_mfma_f32_16x16x32_bf16 v[74:77], v[66:69], v[182:185], v[74:77]
	v_mfma_f32_16x16x32_bf16 v[50:53], v[58:61], v[190:193], v[50:53]
	v_mfma_f32_16x16x32_bf16 v[46:49], v[66:69], v[190:193], v[46:49]
	v_mfma_f32_16x16x32_bf16 v[30:33], v[58:61], v[198:201], v[30:33]
	v_mfma_f32_16x16x32_bf16 v[26:29], v[66:69], v[198:201], v[26:29]
	v_mfma_f32_16x16x32_bf16 v[14:17], v[58:61], v[206:209], v[14:17]
	v_mfma_f32_16x16x32_bf16 v[10:13], v[66:69], v[206:209], v[10:13]
	v_mfma_f32_16x16x32_bf16 v[78:81], v[62:65], v[186:189], v[78:81]
	v_mfma_f32_16x16x32_bf16 v[74:77], v[70:73], v[186:189], v[74:77]
	v_mfma_f32_16x16x32_bf16 v[50:53], v[62:65], v[194:197], v[50:53]
	v_mfma_f32_16x16x32_bf16 v[46:49], v[70:73], v[194:197], v[46:49]
	v_mfma_f32_16x16x32_bf16 v[30:33], v[62:65], v[202:205], v[30:33]
	v_mfma_f32_16x16x32_bf16 v[26:29], v[70:73], v[202:205], v[26:29]
	v_mfma_f32_16x16x32_bf16 v[14:17], v[62:65], v[210:213], v[14:17]
	v_mfma_f32_16x16x32_bf16 v[10:13], v[70:73], v[210:213], v[10:13]
	v_mfma_f32_16x16x32_bf16 v[42:45], v[158:161], v[182:185], v[42:45]
	v_mfma_f32_16x16x32_bf16 v[70:73], v[170:173], v[186:189], v[42:45]
	v_mfma_f32_16x16x32_bf16 v[42:45], v[174:177], v[182:185], v[54:57]
	v_mfma_f32_16x16x32_bf16 v[38:41], v[158:161], v[190:193], v[38:41]
	v_mfma_f32_16x16x32_bf16 v[34:37], v[174:177], v[190:193], v[34:37]
	v_mfma_f32_16x16x32_bf16 v[22:25], v[158:161], v[198:201], v[22:25]
	v_mfma_f32_16x16x32_bf16 v[18:21], v[174:177], v[198:201], v[18:21]
	v_mfma_f32_16x16x32_bf16 v[6:9], v[158:161], v[206:209], v[6:9]
	v_mfma_f32_16x16x32_bf16 v[2:5], v[174:177], v[206:209], v[2:5]
	v_mfma_f32_16x16x32_bf16 v[66:69], v[178:181], v[186:189], v[42:45]
	v_mfma_f32_16x16x32_bf16 v[38:41], v[170:173], v[194:197], v[38:41]
	v_mfma_f32_16x16x32_bf16 v[34:37], v[178:181], v[194:197], v[34:37]
	v_mfma_f32_16x16x32_bf16 v[22:25], v[170:173], v[202:205], v[22:25]
	v_mfma_f32_16x16x32_bf16 v[18:21], v[178:181], v[202:205], v[18:21]
	v_mfma_f32_16x16x32_bf16 v[6:9], v[170:173], v[210:213], v[6:9]
	v_mfma_f32_16x16x32_bf16 v[2:5], v[178:181], v[210:213], v[2:5]
	s_setprio 0
	s_barrier
	s_add_i32 s38, s38, 2
	s_add_u32 s48, s48, 0x100
	s_addc_u32 s49, s49, 0
	s_cmp_gt_u32 s38, 41
	s_mov_b64 s[16:17], s[18:19]
	s_cbranch_scc0 .LBB0_1341
	s_and_b64 vcc, exec, s[12:13]
	s_cbranch_vccz .LBB0_1344
	s_barrier

.LBB0_1459:
	ds_read_b128 v[96:99], v184
	ds_read_b128 v[100:103], v184 offset:1024
	ds_read_b128 v[104:107], v184 offset:2048
	ds_read_b128 v[108:111], v184 offset:3072
	ds_read_b128 v[158:161], v185
	ds_read_b128 v[162:165], v185 offset:1024
	ds_read_b128 v[166:169], v185 offset:2048
	ds_read_b128 v[170:173], v185 offset:3072
	s_add_u32 s4, s24, 0x100
	s_addc_u32 s5, s25, 0
	s_cmp_eq_u32 s50, 40
	s_cselect_b32 s29, s19, s5
	s_cselect_b32 s28, s18, s4
	s_cselect_b32 s27, s21, s49
	s_cselect_b32 s26, s20, s23
	v_lshl_add_u64 v[178:179], s[24:25], 0, v[150:151]
	s_add_i32 m0, s34, 0xc000
	ds_read_b128 v[174:177], v186
	ds_read_b128 v[190:193], v186 offset:1024
	ds_read_b128 v[194:197], v186 offset:2048
	ds_read_b128 v[198:201], v186 offset:3072
	ds_read_b128 v[202:205], v186 offset:4096
	ds_read_b128 v[206:209], v186 offset:5120
	ds_read_b128 v[210:213], v186 offset:6144
	ds_read_b128 v[214:217], v186 offset:7168
	global_load_lds_dwordx4 v[178:179], off
	v_lshl_add_u64 v[178:179], s[24:25], 0, v[152:153]
	s_add_i32 m0, s34, 0xe000
	s_nop 0
	global_load_lds_dwordx4 v[178:179], off
	s_waitcnt vmcnt(8)
	s_waitcnt lgkmcnt(0)
	s_barrier
	s_setprio 1
	v_mfma_f32_16x16x32_bf16 v[140:143], v[96:99], v[174:177], v[140:143]
	v_mfma_f32_16x16x32_bf16 v[136:139], v[104:107], v[174:177], v[136:139]
	v_mfma_f32_16x16x32_bf16 v[124:127], v[96:99], v[194:197], v[124:127]
	v_mfma_f32_16x16x32_bf16 v[120:123], v[104:107], v[194:197], v[120:123]
	v_mfma_f32_16x16x32_bf16 v[92:95], v[96:99], v[202:205], v[92:95]
	v_mfma_f32_16x16x32_bf16 v[88:91], v[104:107], v[202:205], v[88:91]
	v_mfma_f32_16x16x32_bf16 v[76:79], v[96:99], v[210:213], v[76:79]
	v_mfma_f32_16x16x32_bf16 v[72:75], v[104:107], v[210:213], v[72:75]
	v_mfma_f32_16x16x32_bf16 v[140:143], v[100:103], v[190:193], v[140:143]
	v_mfma_f32_16x16x32_bf16 v[136:139], v[108:111], v[190:193], v[136:139]
	v_mfma_f32_16x16x32_bf16 v[124:127], v[100:103], v[198:201], v[124:127]
	v_mfma_f32_16x16x32_bf16 v[120:123], v[108:111], v[198:201], v[120:123]
	v_mfma_f32_16x16x32_bf16 v[92:95], v[100:103], v[206:209], v[92:95]
	v_mfma_f32_16x16x32_bf16 v[88:91], v[108:111], v[206:209], v[88:91]
	v_mfma_f32_16x16x32_bf16 v[76:79], v[100:103], v[214:217], v[76:79]
	v_mfma_f32_16x16x32_bf16 v[72:75], v[108:111], v[214:217], v[72:75]
	v_mfma_f32_16x16x32_bf16 v[132:135], v[158:161], v[174:177], v[132:135]
	v_mfma_f32_16x16x32_bf16 v[128:131], v[166:169], v[174:177], v[128:131]
	v_mfma_f32_16x16x32_bf16 v[116:119], v[158:161], v[194:197], v[116:119]
	v_mfma_f32_16x16x32_bf16 v[112:115], v[166:169], v[194:197], v[112:115]
	v_mfma_f32_16x16x32_bf16 v[84:87], v[158:161], v[202:205], v[84:87]
	v_mfma_f32_16x16x32_bf16 v[80:83], v[166:169], v[202:205], v[80:83]
	v_mfma_f32_16x16x32_bf16 v[68:71], v[158:161], v[210:213], v[68:71]
	v_mfma_f32_16x16x32_bf16 v[64:67], v[166:169], v[210:213], v[64:67]
	v_mfma_f32_16x16x32_bf16 v[132:135], v[162:165], v[190:193], v[132:135]
	v_mfma_f32_16x16x32_bf16 v[128:131], v[170:173], v[190:193], v[128:131]
	v_mfma_f32_16x16x32_bf16 v[116:119], v[162:165], v[198:201], v[116:119]
	v_mfma_f32_16x16x32_bf16 v[112:115], v[170:173], v[198:201], v[112:115]
	v_mfma_f32_16x16x32_bf16 v[84:87], v[162:165], v[206:209], v[84:87]
	v_mfma_f32_16x16x32_bf16 v[80:83], v[170:173], v[206:209], v[80:83]
	v_mfma_f32_16x16x32_bf16 v[68:71], v[162:165], v[214:217], v[68:71]
	v_mfma_f32_16x16x32_bf16 v[64:67], v[170:173], v[214:217], v[64:67]
	s_setprio 0
	s_barrier
	s_add_i32 s24, s43, s33
	v_lshl_add_u64 v[178:179], s[26:27], 0, v[144:145]
	s_mov_b32 m0, s24
	ds_read_b128 v[174:177], v186 offset:16384
	ds_read_b128 v[190:193], v186 offset:17408
	ds_read_b128 v[194:197], v186 offset:18432
	ds_read_b128 v[198:201], v186 offset:19456
	ds_read_b128 v[202:205], v186 offset:20480
	ds_read_b128 v[206:209], v186 offset:21504
	ds_read_b128 v[210:213], v186 offset:22528
	ds_read_b128 v[214:217], v186 offset:23552
	global_load_lds_dwordx4 v[178:179], off
	s_add_i32 m0, s24, 0x2000
	s_add_u32 s24, s26, 0xb0000
	v_lshl_add_u64 v[220:221], s[26:27], 0, v[146:147]
	s_addc_u32 s25, s27, 0
	s_add_i32 s51, s44, s33
	global_load_lds_dwordx4 v[220:221], off
	v_lshl_add_u64 v[222:223], s[24:25], 0, v[144:145]
	s_mov_b32 m0, s51
	v_lshl_add_u64 v[224:225], s[28:29], 0, v[146:147]
	global_load_lds_dwordx4 v[222:223], off
	v_lshl_add_u64 v[222:223], s[24:25], 0, v[146:147]
	s_add_i32 m0, s51, 0x2000
	s_nop 0
	global_load_lds_dwordx4 v[222:223], off
	v_lshl_add_u64 v[222:223], s[28:29], 0, v[144:145]
	s_mov_b32 m0, s34
	s_nop 0
	global_load_lds_dwordx4 v[222:223], off
	s_mov_b32 m0, s35
	s_nop 0
	global_load_lds_dwordx4 v[224:225], off
	s_waitcnt vmcnt(8)
	s_waitcnt lgkmcnt(0)
	s_barrier
	s_setprio 1
	v_mfma_f32_16x16x32_bf16 v[60:63], v[96:99], v[174:177], v[60:63]
	v_mfma_f32_16x16x32_bf16 v[56:59], v[104:107], v[174:177], v[56:59]
	v_mfma_f32_16x16x32_bf16 v[44:47], v[96:99], v[194:197], v[44:47]
	v_mfma_f32_16x16x32_bf16 v[40:43], v[104:107], v[194:197], v[40:43]
	v_mfma_f32_16x16x32_bf16 v[28:31], v[96:99], v[202:205], v[28:31]
	v_mfma_f32_16x16x32_bf16 v[24:27], v[104:107], v[202:205], v[24:27]
	v_mfma_f32_16x16x32_bf16 v[12:15], v[96:99], v[210:213], v[12:15]
	v_mfma_f32_16x16x32_bf16 v[8:11], v[104:107], v[210:213], v[8:11]
	v_mfma_f32_16x16x32_bf16 v[60:63], v[100:103], v[190:193], v[60:63]
	v_mfma_f32_16x16x32_bf16 v[56:59], v[108:111], v[190:193], v[56:59]
	v_mfma_f32_16x16x32_bf16 v[44:47], v[100:103], v[198:201], v[44:47]
	v_mfma_f32_16x16x32_bf16 v[40:43], v[108:111], v[198:201], v[40:43]
	v_mfma_f32_16x16x32_bf16 v[28:31], v[100:103], v[206:209], v[28:31]
	v_mfma_f32_16x16x32_bf16 v[24:27], v[108:111], v[206:209], v[24:27]
	v_mfma_f32_16x16x32_bf16 v[12:15], v[100:103], v[214:217], v[12:15]
	v_mfma_f32_16x16x32_bf16 v[8:11], v[108:111], v[214:217], v[8:11]
	v_mfma_f32_16x16x32_bf16 v[52:55], v[158:161], v[174:177], v[52:55]
	v_mfma_f32_16x16x32_bf16 v[48:51], v[166:169], v[174:177], v[48:51]
	v_mfma_f32_16x16x32_bf16 v[36:39], v[158:161], v[194:197], v[36:39]
	v_mfma_f32_16x16x32_bf16 v[32:35], v[166:169], v[194:197], v[32:35]
	v_mfma_f32_16x16x32_bf16 v[20:23], v[158:161], v[202:205], v[20:23]
	v_mfma_f32_16x16x32_bf16 v[16:19], v[166:169], v[202:205], v[16:19]
	v_mfma_f32_16x16x32_bf16 v[4:7], v[158:161], v[210:213], v[4:7]
	v_mfma_f32_16x16x32_bf16 v[0:3], v[166:169], v[210:213], v[0:3]
	v_mfma_f32_16x16x32_bf16 v[52:55], v[162:165], v[190:193], v[52:55]
	v_mfma_f32_16x16x32_bf16 v[48:51], v[170:173], v[190:193], v[48:51]
	v_mfma_f32_16x16x32_bf16 v[36:39], v[162:165], v[198:201], v[36:39]
	v_mfma_f32_16x16x32_bf16 v[32:35], v[170:173], v[198:201], v[32:35]
	v_mfma_f32_16x16x32_bf16 v[20:23], v[162:165], v[206:209], v[20:23]
	v_mfma_f32_16x16x32_bf16 v[16:19], v[170:173], v[206:209], v[16:19]
	v_mfma_f32_16x16x32_bf16 v[4:7], v[162:165], v[214:217], v[4:7]
	v_mfma_f32_16x16x32_bf16 v[0:3], v[170:173], v[214:217], v[0:3]
	s_setprio 0
	s_barrier
	s_add_i32 s51, 0, 0x18000
	s_add_i32 s52, 0, 0x1c000
	v_add_u32_e32 v108, s51, v181
	v_add_u32_e32 v170, s52, v181
	ds_read_b128 v[96:99], v108
	ds_read_b128 v[100:103], v108 offset:1024
	ds_read_b128 v[104:107], v108 offset:2048
	ds_read_b128 v[108:111], v108 offset:3072
	ds_read_b128 v[158:161], v170
	ds_read_b128 v[162:165], v170 offset:1024
	ds_read_b128 v[166:169], v170 offset:2048
	ds_read_b128 v[170:173], v170 offset:3072
	s_add_u32 s24, s28, 0xb0000
	s_addc_u32 s25, s29, 0
	s_mov_b32 m0, s36
	v_lshl_add_u64 v[226:227], s[24:25], 0, v[144:145]
	ds_read_b128 v[174:177], v186 offset:32768
	ds_read_b128 v[190:193], v186 offset:33792
	ds_read_b128 v[194:197], v186 offset:34816
	ds_read_b128 v[198:201], v186 offset:35840
	ds_read_b128 v[202:205], v186 offset:36864
	ds_read_b128 v[206:209], v186 offset:37888
	ds_read_b128 v[210:213], v186 offset:38912
	ds_read_b128 v[214:217], v186 offset:39936
	global_load_lds_dwordx4 v[226:227], off
	v_lshl_add_u64 v[226:227], s[24:25], 0, v[146:147]
	s_mov_b32 m0, s37
	s_nop 0
	global_load_lds_dwordx4 v[226:227], off
	s_waitcnt vmcnt(8)
	s_waitcnt lgkmcnt(0)
	s_barrier
	s_setprio 1
	v_mfma_f32_16x16x32_bf16 v[140:143], v[96:99], v[174:177], v[140:143]
	v_mfma_f32_16x16x32_bf16 v[136:139], v[104:107], v[174:177], v[136:139]
	v_mfma_f32_16x16x32_bf16 v[124:127], v[96:99], v[194:197], v[124:127]
	v_mfma_f32_16x16x32_bf16 v[120:123], v[104:107], v[194:197], v[120:123]
	v_mfma_f32_16x16x32_bf16 v[92:95], v[96:99], v[202:205], v[92:95]
	v_mfma_f32_16x16x32_bf16 v[88:91], v[104:107], v[202:205], v[88:91]
	v_mfma_f32_16x16x32_bf16 v[76:79], v[96:99], v[210:213], v[76:79]
	v_mfma_f32_16x16x32_bf16 v[72:75], v[104:107], v[210:213], v[72:75]
	v_mfma_f32_16x16x32_bf16 v[140:143], v[100:103], v[190:193], v[140:143]
	v_mfma_f32_16x16x32_bf16 v[136:139], v[108:111], v[190:193], v[136:139]
	v_mfma_f32_16x16x32_bf16 v[124:127], v[100:103], v[198:201], v[124:127]
	v_mfma_f32_16x16x32_bf16 v[120:123], v[108:111], v[198:201], v[120:123]
	v_mfma_f32_16x16x32_bf16 v[92:95], v[100:103], v[206:209], v[92:95]
	v_mfma_f32_16x16x32_bf16 v[88:91], v[108:111], v[206:209], v[88:91]
	v_mfma_f32_16x16x32_bf16 v[76:79], v[100:103], v[214:217], v[76:79]
	v_mfma_f32_16x16x32_bf16 v[72:75], v[108:111], v[214:217], v[72:75]
	v_mfma_f32_16x16x32_bf16 v[132:135], v[158:161], v[174:177], v[132:135]
	v_mfma_f32_16x16x32_bf16 v[128:131], v[166:169], v[174:177], v[128:131]
	v_mfma_f32_16x16x32_bf16 v[116:119], v[158:161], v[194:197], v[116:119]
	v_mfma_f32_16x16x32_bf16 v[112:115], v[166:169], v[194:197], v[112:115]
	v_mfma_f32_16x16x32_bf16 v[84:87], v[158:161], v[202:205], v[84:87]
	v_mfma_f32_16x16x32_bf16 v[80:83], v[166:169], v[202:205], v[80:83]
	v_mfma_f32_16x16x32_bf16 v[68:71], v[158:161], v[210:213], v[68:71]
	v_mfma_f32_16x16x32_bf16 v[64:67], v[166:169], v[210:213], v[64:67]
	v_mfma_f32_16x16x32_bf16 v[132:135], v[162:165], v[190:193], v[132:135]
	v_mfma_f32_16x16x32_bf16 v[128:131], v[170:173], v[190:193], v[128:131]
	v_mfma_f32_16x16x32_bf16 v[116:119], v[162:165], v[198:201], v[116:119]
	v_mfma_f32_16x16x32_bf16 v[112:115], v[170:173], v[198:201], v[112:115]
	v_mfma_f32_16x16x32_bf16 v[84:87], v[162:165], v[206:209], v[84:87]
	v_mfma_f32_16x16x32_bf16 v[80:83], v[170:173], v[206:209], v[80:83]
	v_mfma_f32_16x16x32_bf16 v[68:71], v[162:165], v[214:217], v[68:71]
	v_mfma_f32_16x16x32_bf16 v[64:67], v[170:173], v[214:217], v[64:67]
	s_setprio 0
	s_barrier
	s_add_i32 s24, s51, s33
	v_lshl_add_u64 v[178:179], v[178:179], 0, s[12:13]
	s_mov_b32 m0, s24
	ds_read_b128 v[174:177], v186 offset:49152
	ds_read_b128 v[190:193], v186 offset:50176
	ds_read_b128 v[194:197], v186 offset:51200
	ds_read_b128 v[198:201], v186 offset:52224
	ds_read_b128 v[202:205], v186 offset:53248
	ds_read_b128 v[206:209], v186 offset:54272
	ds_read_b128 v[210:213], v186 offset:55296
	ds_read_b128 v[214:217], v186 offset:56320
	global_load_lds_dwordx4 v[178:179], off
	s_add_i32 m0, s24, 0x2000
	s_add_u32 s24, s26, 0xb0080
	v_lshl_add_u64 v[178:179], v[220:221], 0, s[12:13]
	s_addc_u32 s25, s27, 0
	s_add_i32 s26, s52, s33
	global_load_lds_dwordx4 v[178:179], off
	v_lshl_add_u64 v[178:179], s[24:25], 0, v[144:145]
	s_mov_b32 m0, s26
	s_nop 0
	global_load_lds_dwordx4 v[178:179], off
	v_lshl_add_u64 v[178:179], s[24:25], 0, v[146:147]
	s_add_i32 m0, s26, 0x2000
	s_nop 0
	global_load_lds_dwordx4 v[178:179], off
	v_lshl_add_u64 v[178:179], v[222:223], 0, s[12:13]
	s_mov_b32 m0, s40
	s_nop 0
	global_load_lds_dwordx4 v[178:179], off
	v_lshl_add_u64 v[178:179], v[224:225], 0, s[12:13]
	s_mov_b32 m0, s41
	s_nop 0
	global_load_lds_dwordx4 v[178:179], off
	s_waitcnt vmcnt(8)
	s_waitcnt lgkmcnt(0)
	s_barrier
	s_setprio 1
	v_mfma_f32_16x16x32_bf16 v[60:63], v[96:99], v[174:177], v[60:63]
	v_mfma_f32_16x16x32_bf16 v[56:59], v[104:107], v[174:177], v[56:59]
	v_mfma_f32_16x16x32_bf16 v[44:47], v[96:99], v[194:197], v[44:47]
	v_mfma_f32_16x16x32_bf16 v[40:43], v[104:107], v[194:197], v[40:43]
	v_mfma_f32_16x16x32_bf16 v[28:31], v[96:99], v[202:205], v[28:31]
	v_mfma_f32_16x16x32_bf16 v[24:27], v[104:107], v[202:205], v[24:27]
	v_mfma_f32_16x16x32_bf16 v[12:15], v[96:99], v[210:213], v[12:15]
	v_mfma_f32_16x16x32_bf16 v[8:11], v[104:107], v[210:213], v[8:11]
	v_mfma_f32_16x16x32_bf16 v[60:63], v[100:103], v[190:193], v[60:63]
	v_mfma_f32_16x16x32_bf16 v[56:59], v[108:111], v[190:193], v[56:59]
	v_mfma_f32_16x16x32_bf16 v[44:47], v[100:103], v[198:201], v[44:47]
	v_mfma_f32_16x16x32_bf16 v[40:43], v[108:111], v[198:201], v[40:43]
	v_mfma_f32_16x16x32_bf16 v[28:31], v[100:103], v[206:209], v[28:31]
	v_mfma_f32_16x16x32_bf16 v[24:27], v[108:111], v[206:209], v[24:27]
	v_mfma_f32_16x16x32_bf16 v[12:15], v[100:103], v[214:217], v[12:15]
	v_mfma_f32_16x16x32_bf16 v[8:11], v[108:111], v[214:217], v[8:11]
	v_mfma_f32_16x16x32_bf16 v[52:55], v[158:161], v[174:177], v[52:55]
	v_mfma_f32_16x16x32_bf16 v[48:51], v[166:169], v[174:177], v[48:51]
	v_mfma_f32_16x16x32_bf16 v[36:39], v[158:161], v[194:197], v[36:39]
	v_mfma_f32_16x16x32_bf16 v[32:35], v[166:169], v[194:197], v[32:35]
	v_mfma_f32_16x16x32_bf16 v[20:23], v[158:161], v[202:205], v[20:23]
	v_mfma_f32_16x16x32_bf16 v[16:19], v[166:169], v[202:205], v[16:19]
	v_mfma_f32_16x16x32_bf16 v[4:7], v[158:161], v[210:213], v[4:7]
	v_mfma_f32_16x16x32_bf16 v[0:3], v[166:169], v[210:213], v[0:3]
	v_mfma_f32_16x16x32_bf16 v[52:55], v[162:165], v[190:193], v[52:55]
	v_mfma_f32_16x16x32_bf16 v[48:51], v[170:173], v[190:193], v[48:51]
	v_mfma_f32_16x16x32_bf16 v[36:39], v[162:165], v[198:201], v[36:39]
	v_mfma_f32_16x16x32_bf16 v[32:35], v[170:173], v[198:201], v[32:35]
	v_mfma_f32_16x16x32_bf16 v[20:23], v[162:165], v[206:209], v[20:23]
	v_mfma_f32_16x16x32_bf16 v[16:19], v[170:173], v[206:209], v[16:19]
	v_mfma_f32_16x16x32_bf16 v[4:7], v[162:165], v[214:217], v[4:7]
	v_mfma_f32_16x16x32_bf16 v[0:3], v[170:173], v[214:217], v[0:3]
	s_setprio 0
	s_barrier
	s_add_i32 s50, s50, 2
	s_add_u32 s23, s23, 0x100
	s_addc_u32 s49, s49, 0
	s_cmp_gt_u32 s50, 41
	s_mov_b64 s[24:25], s[4:5]
	s_cbranch_scc0 .LBB0_1459
	s_and_b64 vcc, exec, s[14:15]
	s_cbranch_vccz .LBB0_1462
	s_barrier
